# static s_setprio 1 for waves 4-7 at entry, all per-phase setprio flips deleted (on top of nt P0 loads)
# baseline (speedup 1.0000x reference)
_Z10fwd_kernel4Args:
	s_load_dwordx2 s[48:49], s[0:1], 0x118
	s_load_dword s33, s[0:1], 0x120
	v_bfe_u32 v1, v0, 6, 4
	s_add_u32 s78, s0, 0x118
	v_and_b32_e32 v27, 0x3ff, v0
	v_readfirstlane_b32 s3, v1
	s_addc_u32 s79, s1, 0
	s_cmp_ge_u32 s3, 4
	s_cbranch_scc0 .Lprio_done
	s_setprio 1
.Lprio_done:
	v_cmp_gt_u32_e32 vcc, 2, v27
	v_writelane_b32 v254, s3, 0
	s_and_saveexec_b64 s[4:5], vcc
	v_lshl_add_u32 v2, v27, 2, 0
	v_add_u32_e32 v2, 0x23fc0, v2
	v_mov_b32_e32 v3, 0
	ds_write_b32 v2, v3
	s_or_b64 exec, exec, s[4:5]
	s_waitcnt lgkmcnt(0)
	s_barrier
	v_cmp_eq_u32_e64 s[6:7], 0, v27
	s_mov_b64 s[4:5], exec
	s_nop 0
	v_writelane_b32 v254, s6, 1
	s_nop 1
	v_writelane_b32 v254, s7, 2
	s_and_b64 s[6:7], s[4:5], s[6:7]
	s_mov_b64 exec, s[6:7]
	s_cbranch_execz .LBB0_5
	s_mov_b64 s[6:7], exec
	v_mbcnt_lo_u32_b32 v2, s6, 0
	v_mbcnt_hi_u32_b32 v2, s7, v2
	v_cmp_eq_u32_e32 vcc, 0, v2
	s_getreg_b32 s3, hwreg(HW_REG_XCC_ID, 0, 4)
	s_and_b64 s[8:9], exec, vcc
	s_mov_b64 exec, s[8:9]
	s_cbranch_execz .LBB0_5
	s_load_dwordx2 s[8:9], s[0:1], 0x108
	s_lshl_b32 s3, s3, 8
	s_and_b32 s3, s3, 0xf00
	v_mov_b32_e32 v2, 0x10000
	s_waitcnt lgkmcnt(0)
	s_add_u32 s8, s8, s3
	s_addc_u32 s9, s9, 0
	s_bcnt1_i32_b64 s3, s[6:7]
	v_mov_b32_e32 v3, s3
	global_atomic_add v2, v3, s[8:9] offset:1024

.LBB0_303:
	s_add_u32 s12, s4, 0xfffc0080
	s_addc_u32 s13, s5, -1
	s_add_i32 s40, 0, 0x10000
	s_cmp_eq_u32 s38, 12
	s_cselect_b32 s15, s17, s13
	s_cselect_b32 s14, s18, s12
	s_cselect_b32 s13, s19, s37
	s_cselect_b32 s12, s23, s36
	s_add_i32 s42, 0, 0x14000
	v_add_u32_e32 v44, s40, v170
	v_add_u32_e32 v179, s42, v170
	ds_read_b128 v[24:27], v44
	ds_read_b128 v[28:31], v44 offset:1024
	ds_read_b128 v[40:43], v44 offset:2048
	ds_read_b128 v[44:47], v44 offset:3072
	ds_read_b128 v[158:161], v179
	ds_read_b128 v[162:165], v179 offset:1024
	ds_read_b128 v[166:169], v179 offset:2048
	ds_read_b128 v[180:183], v179 offset:3072
	v_lshl_add_u64 v[218:219], s[4:5], 0, v[154:155]
	s_add_i32 m0, s7, 0xc000
	ds_read_b128 v[184:187], v178
	ds_read_b128 v[188:191], v178 offset:1024
	ds_read_b128 v[192:195], v178 offset:2048
	ds_read_b128 v[196:199], v178 offset:3072
	ds_read_b128 v[202:205], v178 offset:4096
	ds_read_b128 v[206:209], v178 offset:5120
	ds_read_b128 v[210:213], v178 offset:6144
	ds_read_b128 v[214:217], v178 offset:7168
	global_load_lds_dwordx4 v[218:219], off
	v_lshl_add_u64 v[218:219], s[4:5], 0, v[156:157]
	s_add_i32 m0, s7, 0xe000
	s_nop 0
	global_load_lds_dwordx4 v[218:219], off
	s_waitcnt vmcnt(8)
	s_waitcnt lgkmcnt(0)
	s_barrier
	s_waitcnt lgkmcnt(0)
	v_mfma_f32_16x16x32_bf16 v[140:143], v[24:27], v[184:187], v[140:143]
	v_mfma_f32_16x16x32_bf16 v[136:139], v[40:43], v[184:187], v[136:139]
	v_mfma_f32_16x16x32_bf16 v[124:127], v[24:27], v[192:195], v[124:127]
	v_mfma_f32_16x16x32_bf16 v[120:123], v[40:43], v[192:195], v[120:123]
	v_mfma_f32_16x16x32_bf16 v[108:111], v[24:27], v[202:205], v[108:111]
	v_mfma_f32_16x16x32_bf16 v[104:107], v[40:43], v[202:205], v[104:107]
	v_mfma_f32_16x16x32_bf16 v[92:95], v[24:27], v[210:213], v[92:95]
	v_mfma_f32_16x16x32_bf16 v[88:91], v[40:43], v[210:213], v[88:91]
	v_mfma_f32_16x16x32_bf16 v[140:143], v[28:31], v[188:191], v[140:143]
	v_mfma_f32_16x16x32_bf16 v[136:139], v[44:47], v[188:191], v[136:139]
	v_mfma_f32_16x16x32_bf16 v[124:127], v[28:31], v[196:199], v[124:127]
	v_mfma_f32_16x16x32_bf16 v[120:123], v[44:47], v[196:199], v[120:123]
	v_mfma_f32_16x16x32_bf16 v[108:111], v[28:31], v[206:209], v[108:111]
	v_mfma_f32_16x16x32_bf16 v[104:107], v[44:47], v[206:209], v[104:107]
	v_mfma_f32_16x16x32_bf16 v[92:95], v[28:31], v[214:217], v[92:95]
	v_mfma_f32_16x16x32_bf16 v[88:91], v[44:47], v[214:217], v[88:91]
	v_mfma_f32_16x16x32_bf16 v[132:135], v[158:161], v[184:187], v[132:135]
	v_mfma_f32_16x16x32_bf16 v[128:131], v[166:169], v[184:187], v[128:131]
	v_mfma_f32_16x16x32_bf16 v[116:119], v[158:161], v[192:195], v[116:119]
	v_mfma_f32_16x16x32_bf16 v[112:115], v[166:169], v[192:195], v[112:115]
	v_mfma_f32_16x16x32_bf16 v[100:103], v[158:161], v[202:205], v[100:103]
	v_mfma_f32_16x16x32_bf16 v[96:99], v[166:169], v[202:205], v[96:99]
	v_mfma_f32_16x16x32_bf16 v[84:87], v[158:161], v[210:213], v[84:87]
	v_mfma_f32_16x16x32_bf16 v[80:83], v[166:169], v[210:213], v[80:83]
	v_mfma_f32_16x16x32_bf16 v[132:135], v[162:165], v[188:191], v[132:135]
	v_mfma_f32_16x16x32_bf16 v[128:131], v[180:183], v[188:191], v[128:131]
	v_mfma_f32_16x16x32_bf16 v[116:119], v[162:165], v[196:199], v[116:119]
	v_mfma_f32_16x16x32_bf16 v[112:115], v[180:183], v[196:199], v[112:115]
	v_mfma_f32_16x16x32_bf16 v[100:103], v[162:165], v[206:209], v[100:103]
	v_mfma_f32_16x16x32_bf16 v[96:99], v[180:183], v[206:209], v[96:99]
	v_mfma_f32_16x16x32_bf16 v[84:87], v[162:165], v[214:217], v[84:87]
	v_mfma_f32_16x16x32_bf16 v[80:83], v[180:183], v[214:217], v[80:83]
	s_barrier
	s_add_i32 s40, s40, s6
	v_lshl_add_u64 v[218:219], s[12:13], 0, v[148:149]
	s_mov_b32 m0, s40
	ds_read_b128 v[184:187], v178 offset:16384
	ds_read_b128 v[188:191], v178 offset:17408
	ds_read_b128 v[192:195], v178 offset:18432
	ds_read_b128 v[196:199], v178 offset:19456
	ds_read_b128 v[202:205], v178 offset:20480
	ds_read_b128 v[206:209], v178 offset:21504
	ds_read_b128 v[210:213], v178 offset:22528
	ds_read_b128 v[214:217], v178 offset:23552
	global_load_lds_dwordx4 v[218:219], off
	s_add_i32 m0, s40, 0x2000
	s_add_u32 s40, s12, 0x40000
	v_lshl_add_u64 v[220:221], s[12:13], 0, v[144:145]
	s_addc_u32 s41, s13, 0
	s_add_i32 s42, s42, s6
	global_load_lds_dwordx4 v[220:221], off
	v_lshl_add_u64 v[222:223], s[40:41], 0, v[148:149]
	s_mov_b32 m0, s42
	v_lshl_add_u64 v[224:225], s[14:15], 0, v[146:147]
	global_load_lds_dwordx4 v[222:223], off
	v_lshl_add_u64 v[222:223], s[40:41], 0, v[144:145]
	s_add_i32 m0, s42, 0x2000
	s_nop 0
	global_load_lds_dwordx4 v[222:223], off
	v_lshl_add_u64 v[222:223], s[14:15], 0, v[150:151]
	s_mov_b32 m0, s7
	s_nop 0
	global_load_lds_dwordx4 v[222:223], off
	s_mov_b32 m0, s83
	s_nop 0
	global_load_lds_dwordx4 v[224:225], off
	s_waitcnt vmcnt(8)
	s_waitcnt lgkmcnt(0)
	s_barrier
	s_waitcnt lgkmcnt(0)
	v_mfma_f32_16x16x32_bf16 v[76:79], v[24:27], v[184:187], v[76:79]
	v_mfma_f32_16x16x32_bf16 v[72:75], v[40:43], v[184:187], v[72:75]
	v_mfma_f32_16x16x32_bf16 v[60:63], v[24:27], v[192:195], v[60:63]
	v_mfma_f32_16x16x32_bf16 v[56:59], v[40:43], v[192:195], v[56:59]
	v_mfma_f32_16x16x32_bf16 v[36:39], v[24:27], v[202:205], v[36:39]
	v_mfma_f32_16x16x32_bf16 v[32:35], v[40:43], v[202:205], v[32:35]
	v_mfma_f32_16x16x32_bf16 v[12:15], v[24:27], v[210:213], v[12:15]
	v_mfma_f32_16x16x32_bf16 v[8:11], v[40:43], v[210:213], v[8:11]
	v_mfma_f32_16x16x32_bf16 v[76:79], v[28:31], v[188:191], v[76:79]
	v_mfma_f32_16x16x32_bf16 v[72:75], v[44:47], v[188:191], v[72:75]
	v_mfma_f32_16x16x32_bf16 v[60:63], v[28:31], v[196:199], v[60:63]
	v_mfma_f32_16x16x32_bf16 v[56:59], v[44:47], v[196:199], v[56:59]
	v_mfma_f32_16x16x32_bf16 v[36:39], v[28:31], v[206:209], v[36:39]
	v_mfma_f32_16x16x32_bf16 v[32:35], v[44:47], v[206:209], v[32:35]
	v_mfma_f32_16x16x32_bf16 v[12:15], v[28:31], v[214:217], v[12:15]
	v_mfma_f32_16x16x32_bf16 v[8:11], v[44:47], v[214:217], v[8:11]
	v_mfma_f32_16x16x32_bf16 v[20:23], v[158:161], v[202:205], v[20:23]
	v_mfma_f32_16x16x32_bf16 v[16:19], v[166:169], v[202:205], v[16:19]
	v_mfma_f32_16x16x32_bf16 v[4:7], v[158:161], v[210:213], v[4:7]
	v_mfma_f32_16x16x32_bf16 v[0:3], v[166:169], v[210:213], v[0:3]
	v_mfma_f32_16x16x32_bf16 v[24:27], v[158:161], v[184:187], v[68:71]
	v_mfma_f32_16x16x32_bf16 v[28:31], v[166:169], v[184:187], v[64:67]
	v_mfma_f32_16x16x32_bf16 v[40:43], v[158:161], v[192:195], v[52:55]
	v_mfma_f32_16x16x32_bf16 v[44:47], v[166:169], v[192:195], v[48:51]
	v_mfma_f32_16x16x32_bf16 v[20:23], v[162:165], v[206:209], v[20:23]
	v_mfma_f32_16x16x32_bf16 v[16:19], v[180:183], v[206:209], v[16:19]
	v_mfma_f32_16x16x32_bf16 v[4:7], v[162:165], v[214:217], v[4:7]
	v_mfma_f32_16x16x32_bf16 v[0:3], v[180:183], v[214:217], v[0:3]
	v_mfma_f32_16x16x32_bf16 v[24:27], v[162:165], v[188:191], v[24:27]
	v_mfma_f32_16x16x32_bf16 v[28:31], v[180:183], v[188:191], v[28:31]
	v_mfma_f32_16x16x32_bf16 v[40:43], v[162:165], v[196:199], v[40:43]
	v_mfma_f32_16x16x32_bf16 v[44:47], v[180:183], v[196:199], v[44:47]
	s_barrier
	s_add_i32 s40, 0, 0x18000
	s_add_i32 s41, 0, 0x1c000
	v_add_u32_e32 v68, s40, v170
	v_add_u32_e32 v179, s41, v170
	ds_read_b128 v[48:51], v68
	ds_read_b128 v[52:55], v68 offset:1024
	ds_read_b128 v[64:67], v68 offset:2048
	ds_read_b128 v[68:71], v68 offset:3072
	ds_read_b128 v[158:161], v179
	ds_read_b128 v[162:165], v179 offset:1024
	ds_read_b128 v[166:169], v179 offset:2048
	ds_read_b128 v[180:183], v179 offset:3072
	s_add_u32 s14, s14, 0x40000
	s_addc_u32 s15, s15, 0
	s_mov_b32 m0, s84
	v_lshl_add_u64 v[226:227], s[14:15], 0, v[150:151]
	ds_read_b128 v[184:187], v178 offset:32768
	ds_read_b128 v[188:191], v178 offset:33792
	ds_read_b128 v[192:195], v178 offset:34816
	ds_read_b128 v[196:199], v178 offset:35840
	ds_read_b128 v[202:205], v178 offset:36864
	ds_read_b128 v[206:209], v178 offset:37888
	ds_read_b128 v[210:213], v178 offset:38912
	ds_read_b128 v[214:217], v178 offset:39936
	global_load_lds_dwordx4 v[226:227], off
	v_lshl_add_u64 v[226:227], s[14:15], 0, v[146:147]
	s_mov_b32 m0, s85
	s_nop 0
	global_load_lds_dwordx4 v[226:227], off
	s_waitcnt vmcnt(8)
	s_waitcnt lgkmcnt(0)
	s_barrier
	s_waitcnt lgkmcnt(0)
	v_mfma_f32_16x16x32_bf16 v[140:143], v[48:51], v[184:187], v[140:143]
	v_mfma_f32_16x16x32_bf16 v[136:139], v[64:67], v[184:187], v[136:139]
	v_mfma_f32_16x16x32_bf16 v[124:127], v[48:51], v[192:195], v[124:127]
	v_mfma_f32_16x16x32_bf16 v[120:123], v[64:67], v[192:195], v[120:123]
	v_mfma_f32_16x16x32_bf16 v[108:111], v[48:51], v[202:205], v[108:111]
	v_mfma_f32_16x16x32_bf16 v[104:107], v[64:67], v[202:205], v[104:107]
	v_mfma_f32_16x16x32_bf16 v[92:95], v[48:51], v[210:213], v[92:95]
	v_mfma_f32_16x16x32_bf16 v[88:91], v[64:67], v[210:213], v[88:91]
	v_mfma_f32_16x16x32_bf16 v[140:143], v[52:55], v[188:191], v[140:143]
	v_mfma_f32_16x16x32_bf16 v[136:139], v[68:71], v[188:191], v[136:139]
	v_mfma_f32_16x16x32_bf16 v[124:127], v[52:55], v[196:199], v[124:127]
	v_mfma_f32_16x16x32_bf16 v[120:123], v[68:71], v[196:199], v[120:123]
	v_mfma_f32_16x16x32_bf16 v[108:111], v[52:55], v[206:209], v[108:111]
	v_mfma_f32_16x16x32_bf16 v[104:107], v[68:71], v[206:209], v[104:107]
	v_mfma_f32_16x16x32_bf16 v[92:95], v[52:55], v[214:217], v[92:95]
	v_mfma_f32_16x16x32_bf16 v[88:91], v[68:71], v[214:217], v[88:91]
	v_mfma_f32_16x16x32_bf16 v[132:135], v[158:161], v[184:187], v[132:135]
	v_mfma_f32_16x16x32_bf16 v[128:131], v[166:169], v[184:187], v[128:131]
	v_mfma_f32_16x16x32_bf16 v[116:119], v[158:161], v[192:195], v[116:119]
	v_mfma_f32_16x16x32_bf16 v[112:115], v[166:169], v[192:195], v[112:115]
	v_mfma_f32_16x16x32_bf16 v[100:103], v[158:161], v[202:205], v[100:103]
	v_mfma_f32_16x16x32_bf16 v[96:99], v[166:169], v[202:205], v[96:99]
	v_mfma_f32_16x16x32_bf16 v[84:87], v[158:161], v[210:213], v[84:87]
	v_mfma_f32_16x16x32_bf16 v[80:83], v[166:169], v[210:213], v[80:83]
	v_mfma_f32_16x16x32_bf16 v[132:135], v[162:165], v[188:191], v[132:135]
	v_mfma_f32_16x16x32_bf16 v[128:131], v[180:183], v[188:191], v[128:131]
	v_mfma_f32_16x16x32_bf16 v[116:119], v[162:165], v[196:199], v[116:119]
	v_mfma_f32_16x16x32_bf16 v[112:115], v[180:183], v[196:199], v[112:115]
	v_mfma_f32_16x16x32_bf16 v[100:103], v[162:165], v[206:209], v[100:103]
	v_mfma_f32_16x16x32_bf16 v[96:99], v[180:183], v[206:209], v[96:99]
	v_mfma_f32_16x16x32_bf16 v[84:87], v[162:165], v[214:217], v[84:87]
	v_mfma_f32_16x16x32_bf16 v[80:83], v[180:183], v[214:217], v[80:83]
	s_barrier
	s_add_i32 s14, s40, s6
	v_lshl_add_u64 v[218:219], v[218:219], 0, s[20:21]
	s_mov_b32 m0, s14
	ds_read_b128 v[184:187], v178 offset:49152
	ds_read_b128 v[188:191], v178 offset:50176
	ds_read_b128 v[192:195], v178 offset:51200
	ds_read_b128 v[196:199], v178 offset:52224
	ds_read_b128 v[202:205], v178 offset:53248
	ds_read_b128 v[206:209], v178 offset:54272
	ds_read_b128 v[210:213], v178 offset:55296
	ds_read_b128 v[214:217], v178 offset:56320
	global_load_lds_dwordx4 v[218:219], off
	s_add_i32 m0, s14, 0x2000
	s_add_u32 s12, s12, 0x40080
	v_lshl_add_u64 v[218:219], v[220:221], 0, s[20:21]
	s_addc_u32 s13, s13, 0
	s_add_i32 s14, s41, s6
	global_load_lds_dwordx4 v[218:219], off
	v_lshl_add_u64 v[218:219], s[12:13], 0, v[148:149]
	s_mov_b32 m0, s14
	s_nop 0
	global_load_lds_dwordx4 v[218:219], off
	v_lshl_add_u64 v[218:219], s[12:13], 0, v[144:145]
	s_add_i32 m0, s14, 0x2000
	s_nop 0
	global_load_lds_dwordx4 v[218:219], off
	v_lshl_add_u64 v[218:219], v[222:223], 0, s[20:21]
	s_mov_b32 m0, s34
	s_nop 0
	global_load_lds_dwordx4 v[218:219], off
	v_lshl_add_u64 v[218:219], v[224:225], 0, s[20:21]
	s_mov_b32 m0, s30
	s_nop 0
	global_load_lds_dwordx4 v[218:219], off
	s_waitcnt vmcnt(8)
	s_waitcnt lgkmcnt(0)
	s_barrier
	s_waitcnt lgkmcnt(0)
	v_mfma_f32_16x16x32_bf16 v[76:79], v[48:51], v[184:187], v[76:79]
	v_mfma_f32_16x16x32_bf16 v[72:75], v[64:67], v[184:187], v[72:75]
	v_mfma_f32_16x16x32_bf16 v[60:63], v[48:51], v[192:195], v[60:63]
	v_mfma_f32_16x16x32_bf16 v[56:59], v[64:67], v[192:195], v[56:59]
	v_mfma_f32_16x16x32_bf16 v[36:39], v[48:51], v[202:205], v[36:39]
	v_mfma_f32_16x16x32_bf16 v[32:35], v[64:67], v[202:205], v[32:35]
	v_mfma_f32_16x16x32_bf16 v[12:15], v[48:51], v[210:213], v[12:15]
	v_mfma_f32_16x16x32_bf16 v[8:11], v[64:67], v[210:213], v[8:11]
	v_mfma_f32_16x16x32_bf16 v[76:79], v[52:55], v[188:191], v[76:79]
	v_mfma_f32_16x16x32_bf16 v[72:75], v[68:71], v[188:191], v[72:75]
	v_mfma_f32_16x16x32_bf16 v[60:63], v[52:55], v[196:199], v[60:63]
	v_mfma_f32_16x16x32_bf16 v[56:59], v[68:71], v[196:199], v[56:59]
	v_mfma_f32_16x16x32_bf16 v[36:39], v[52:55], v[206:209], v[36:39]
	v_mfma_f32_16x16x32_bf16 v[32:35], v[68:71], v[206:209], v[32:35]
	v_mfma_f32_16x16x32_bf16 v[12:15], v[52:55], v[214:217], v[12:15]
	v_mfma_f32_16x16x32_bf16 v[8:11], v[68:71], v[214:217], v[8:11]
	v_mfma_f32_16x16x32_bf16 v[24:27], v[158:161], v[184:187], v[24:27]
	v_mfma_f32_16x16x32_bf16 v[68:71], v[162:165], v[188:191], v[24:27]
	v_mfma_f32_16x16x32_bf16 v[24:27], v[166:169], v[184:187], v[28:31]
	v_mfma_f32_16x16x32_bf16 v[64:67], v[180:183], v[188:191], v[24:27]
	v_mfma_f32_16x16x32_bf16 v[24:27], v[158:161], v[192:195], v[40:43]
	v_mfma_f32_16x16x32_bf16 v[52:55], v[162:165], v[196:199], v[24:27]
	v_mfma_f32_16x16x32_bf16 v[24:27], v[166:169], v[192:195], v[44:47]
	v_mfma_f32_16x16x32_bf16 v[20:23], v[158:161], v[202:205], v[20:23]
	v_mfma_f32_16x16x32_bf16 v[16:19], v[166:169], v[202:205], v[16:19]
	v_mfma_f32_16x16x32_bf16 v[4:7], v[158:161], v[210:213], v[4:7]
	v_mfma_f32_16x16x32_bf16 v[0:3], v[166:169], v[210:213], v[0:3]
	v_mfma_f32_16x16x32_bf16 v[48:51], v[180:183], v[196:199], v[24:27]
	v_mfma_f32_16x16x32_bf16 v[20:23], v[162:165], v[206:209], v[20:23]
	v_mfma_f32_16x16x32_bf16 v[16:19], v[180:183], v[206:209], v[16:19]
	v_mfma_f32_16x16x32_bf16 v[4:7], v[162:165], v[214:217], v[4:7]
	v_mfma_f32_16x16x32_bf16 v[0:3], v[180:183], v[214:217], v[0:3]
	s_barrier
	s_add_i32 s38, s38, 2
	s_add_u32 s4, s4, 0x100
	s_addc_u32 s5, s5, 0
	s_add_u32 s36, s36, 0x100
	s_addc_u32 s37, s37, 0
	s_cmp_gt_u32 s38, 13
	s_cbranch_scc0 .LBB0_303
	s_and_b64 vcc, exec, s[92:93]
	s_cbranch_vccz .LBB0_306
	s_barrier

.LBB0_768:
	s_add_u32 s52, s76, 0xfff80080
	s_addc_u32 s53, s77, -1
	s_add_i32 s87, 0, 0x10000
	s_cmp_eq_u32 s86, 28
	s_cselect_b32 s75, s42, s53
	s_cselect_b32 s74, s43, s52
	s_cselect_b32 s53, s25, s73
	s_cselect_b32 s52, s50, s51
	s_add_i32 s94, 0, 0x14000
	v_add_u32_e32 v132, s87, v209
	v_add_u32_e32 v156, s94, v209
	ds_read_b128 v[120:123], v132
	ds_read_b128 v[124:127], v132 offset:1024
	ds_read_b128 v[128:131], v132 offset:2048
	ds_read_b128 v[132:135], v132 offset:3072
	ds_read_b128 v[144:147], v156
	ds_read_b128 v[148:151], v156 offset:1024
	ds_read_b128 v[152:155], v156 offset:2048
	ds_read_b128 v[156:159], v156 offset:3072
	v_lshl_add_u64 v[198:199], s[76:77], 0, v[166:167]
	s_add_i32 m0, s34, 0xc000
	ds_read_b128 v[170:173], v213
	ds_read_b128 v[174:177], v213 offset:1024
	ds_read_b128 v[178:181], v213 offset:2048
	ds_read_b128 v[182:185], v213 offset:3072
	ds_read_b128 v[186:189], v213 offset:4096
	ds_read_b128 v[190:193], v213 offset:5120
	ds_read_b128 v[194:197], v213 offset:6144
	ds_read_b128 v[202:205], v213 offset:7168
	global_load_lds_dwordx4 v[198:199], off
	v_lshl_add_u64 v[198:199], s[76:77], 0, v[168:169]
	s_add_i32 m0, s34, 0xe000
	s_nop 0
	global_load_lds_dwordx4 v[198:199], off
	s_waitcnt vmcnt(8)
	s_waitcnt lgkmcnt(0)
	s_barrier
	s_waitcnt lgkmcnt(0)
	v_mfma_f32_16x16x32_bf16 v[140:143], v[120:123], v[170:173], v[140:143]
	v_mfma_f32_16x16x32_bf16 v[136:139], v[128:131], v[170:173], v[136:139]
	v_mfma_f32_16x16x32_bf16 v[76:79], v[120:123], v[178:181], v[76:79]
	v_mfma_f32_16x16x32_bf16 v[72:75], v[128:131], v[178:181], v[72:75]
	v_mfma_f32_16x16x32_bf16 v[88:91], v[120:123], v[186:189], v[88:91]
	v_mfma_f32_16x16x32_bf16 v[92:95], v[128:131], v[186:189], v[92:95]
	v_mfma_f32_16x16x32_bf16 v[96:99], v[120:123], v[194:197], v[96:99]
	v_mfma_f32_16x16x32_bf16 v[100:103], v[128:131], v[194:197], v[100:103]
	v_mfma_f32_16x16x32_bf16 v[140:143], v[124:127], v[174:177], v[140:143]
	v_mfma_f32_16x16x32_bf16 v[136:139], v[132:135], v[174:177], v[136:139]
	v_mfma_f32_16x16x32_bf16 v[76:79], v[124:127], v[182:185], v[76:79]
	v_mfma_f32_16x16x32_bf16 v[72:75], v[132:135], v[182:185], v[72:75]
	v_mfma_f32_16x16x32_bf16 v[88:91], v[124:127], v[190:193], v[88:91]
	v_mfma_f32_16x16x32_bf16 v[92:95], v[132:135], v[190:193], v[92:95]
	v_mfma_f32_16x16x32_bf16 v[96:99], v[124:127], v[202:205], v[96:99]
	v_mfma_f32_16x16x32_bf16 v[100:103], v[132:135], v[202:205], v[100:103]
	v_mfma_f32_16x16x32_bf16 v[60:63], v[144:147], v[170:173], v[60:63]
	v_mfma_f32_16x16x32_bf16 v[56:59], v[152:155], v[170:173], v[56:59]
	v_mfma_f32_16x16x32_bf16 v[52:55], v[144:147], v[178:181], v[52:55]
	v_mfma_f32_16x16x32_bf16 v[48:51], v[152:155], v[178:181], v[48:51]
	v_mfma_f32_16x16x32_bf16 v[44:47], v[144:147], v[186:189], v[44:47]
	v_mfma_f32_16x16x32_bf16 v[40:43], v[152:155], v[186:189], v[40:43]
	v_mfma_f32_16x16x32_bf16 v[36:39], v[144:147], v[194:197], v[36:39]
	v_mfma_f32_16x16x32_bf16 v[32:35], v[152:155], v[194:197], v[32:35]
	v_mfma_f32_16x16x32_bf16 v[60:63], v[148:151], v[174:177], v[60:63]
	v_mfma_f32_16x16x32_bf16 v[56:59], v[156:159], v[174:177], v[56:59]
	v_mfma_f32_16x16x32_bf16 v[52:55], v[148:151], v[182:185], v[52:55]
	v_mfma_f32_16x16x32_bf16 v[48:51], v[156:159], v[182:185], v[48:51]
	v_mfma_f32_16x16x32_bf16 v[44:47], v[148:151], v[190:193], v[44:47]
	v_mfma_f32_16x16x32_bf16 v[40:43], v[156:159], v[190:193], v[40:43]
	v_mfma_f32_16x16x32_bf16 v[36:39], v[148:151], v[202:205], v[36:39]
	v_mfma_f32_16x16x32_bf16 v[32:35], v[156:159], v[202:205], v[32:35]
	s_barrier
	s_add_i32 s87, s87, s33
	v_lshl_add_u64 v[198:199], s[52:53], 0, v[200:201]
	s_mov_b32 m0, s87
	ds_read_b128 v[170:173], v213 offset:16384
	ds_read_b128 v[174:177], v213 offset:17408
	ds_read_b128 v[178:181], v213 offset:18432
	ds_read_b128 v[182:185], v213 offset:19456
	ds_read_b128 v[186:189], v213 offset:20480
	ds_read_b128 v[190:193], v213 offset:21504
	ds_read_b128 v[194:197], v213 offset:22528
	ds_read_b128 v[202:205], v213 offset:23552
	global_load_lds_dwordx4 v[198:199], off
	s_add_i32 m0, s87, 0x2000
	s_add_u32 s92, s52, 0x80000
	v_lshl_add_u64 v[206:207], s[52:53], 0, v[160:161]
	s_addc_u32 s93, s53, 0
	s_add_i32 s87, s94, s33
	global_load_lds_dwordx4 v[206:207], off
	v_lshl_add_u64 v[214:215], s[92:93], 0, v[200:201]
	s_mov_b32 m0, s87
	v_lshl_add_u64 v[216:217], s[74:75], 0, v[162:163]
	global_load_lds_dwordx4 v[214:215], off
	v_lshl_add_u64 v[214:215], s[92:93], 0, v[160:161]
	s_add_i32 m0, s87, 0x2000
	s_nop 0
	global_load_lds_dwordx4 v[214:215], off
	v_lshl_add_u64 v[214:215], s[74:75], 0, v[164:165]
	s_mov_b32 m0, s34
	s_nop 0
	global_load_lds_dwordx4 v[214:215], off
	s_mov_b32 m0, s36
	s_nop 0
	global_load_lds_dwordx4 v[216:217], off
	s_waitcnt vmcnt(8)
	s_waitcnt lgkmcnt(0)
	s_barrier
	s_waitcnt lgkmcnt(0)
	v_mfma_f32_16x16x32_bf16 v[112:115], v[120:123], v[170:173], v[112:115]
	v_mfma_f32_16x16x32_bf16 v[104:107], v[128:131], v[170:173], v[104:107]
	v_mfma_f32_16x16x32_bf16 v[116:119], v[120:123], v[178:181], v[116:119]
	v_mfma_f32_16x16x32_bf16 v[108:111], v[128:131], v[178:181], v[108:111]
	v_mfma_f32_16x16x32_bf16 v[84:87], v[120:123], v[186:189], v[84:87]
	v_mfma_f32_16x16x32_bf16 v[80:83], v[128:131], v[186:189], v[80:83]
	v_mfma_f32_16x16x32_bf16 v[68:71], v[120:123], v[194:197], v[68:71]
	v_mfma_f32_16x16x32_bf16 v[64:67], v[128:131], v[194:197], v[64:67]
	v_mfma_f32_16x16x32_bf16 v[112:115], v[124:127], v[174:177], v[112:115]
	v_mfma_f32_16x16x32_bf16 v[104:107], v[132:135], v[174:177], v[104:107]
	v_mfma_f32_16x16x32_bf16 v[116:119], v[124:127], v[182:185], v[116:119]
	v_mfma_f32_16x16x32_bf16 v[108:111], v[132:135], v[182:185], v[108:111]
	v_mfma_f32_16x16x32_bf16 v[84:87], v[124:127], v[190:193], v[84:87]
	v_mfma_f32_16x16x32_bf16 v[80:83], v[132:135], v[190:193], v[80:83]
	v_mfma_f32_16x16x32_bf16 v[68:71], v[124:127], v[202:205], v[68:71]
	v_mfma_f32_16x16x32_bf16 v[64:67], v[132:135], v[202:205], v[64:67]
	v_mfma_f32_16x16x32_bf16 v[28:31], v[144:147], v[170:173], v[28:31]
	v_mfma_f32_16x16x32_bf16 v[24:27], v[152:155], v[170:173], v[24:27]
	v_mfma_f32_16x16x32_bf16 v[20:23], v[144:147], v[178:181], v[20:23]
	v_mfma_f32_16x16x32_bf16 v[16:19], v[152:155], v[178:181], v[16:19]
	v_mfma_f32_16x16x32_bf16 v[12:15], v[144:147], v[186:189], v[12:15]
	v_mfma_f32_16x16x32_bf16 v[8:11], v[152:155], v[186:189], v[8:11]
	v_mfma_f32_16x16x32_bf16 v[4:7], v[144:147], v[194:197], v[4:7]
	v_mfma_f32_16x16x32_bf16 v[0:3], v[152:155], v[194:197], v[0:3]
	v_mfma_f32_16x16x32_bf16 v[28:31], v[148:151], v[174:177], v[28:31]
	v_mfma_f32_16x16x32_bf16 v[24:27], v[156:159], v[174:177], v[24:27]
	v_mfma_f32_16x16x32_bf16 v[20:23], v[148:151], v[182:185], v[20:23]
	v_mfma_f32_16x16x32_bf16 v[16:19], v[156:159], v[182:185], v[16:19]
	v_mfma_f32_16x16x32_bf16 v[12:15], v[148:151], v[190:193], v[12:15]
	v_mfma_f32_16x16x32_bf16 v[8:11], v[156:159], v[190:193], v[8:11]
	v_mfma_f32_16x16x32_bf16 v[4:7], v[148:151], v[202:205], v[4:7]
	v_mfma_f32_16x16x32_bf16 v[0:3], v[156:159], v[202:205], v[0:3]
	s_barrier
	s_add_i32 s87, 0, 0x18000
	s_add_i32 s92, 0, 0x1c000
	v_add_u32_e32 v132, s87, v209
	v_add_u32_e32 v156, s92, v209
	ds_read_b128 v[120:123], v132
	ds_read_b128 v[124:127], v132 offset:1024
	ds_read_b128 v[128:131], v132 offset:2048
	ds_read_b128 v[132:135], v132 offset:3072
	ds_read_b128 v[144:147], v156
	ds_read_b128 v[148:151], v156 offset:1024
	ds_read_b128 v[152:155], v156 offset:2048
	ds_read_b128 v[156:159], v156 offset:3072
	s_add_u32 s74, s74, 0x80000
	s_addc_u32 s75, s75, 0
	s_mov_b32 m0, s37
	v_lshl_add_u64 v[218:219], s[74:75], 0, v[164:165]
	ds_read_b128 v[170:173], v213 offset:32768
	ds_read_b128 v[174:177], v213 offset:33792
	ds_read_b128 v[178:181], v213 offset:34816
	ds_read_b128 v[182:185], v213 offset:35840
	ds_read_b128 v[186:189], v213 offset:36864
	ds_read_b128 v[190:193], v213 offset:37888
	ds_read_b128 v[194:197], v213 offset:38912
	ds_read_b128 v[202:205], v213 offset:39936
	global_load_lds_dwordx4 v[218:219], off
	v_lshl_add_u64 v[218:219], s[74:75], 0, v[162:163]
	s_mov_b32 m0, s38
	s_nop 0
	global_load_lds_dwordx4 v[218:219], off
	s_waitcnt vmcnt(8)
	s_waitcnt lgkmcnt(0)
	s_barrier
	s_waitcnt lgkmcnt(0)
	v_mfma_f32_16x16x32_bf16 v[140:143], v[120:123], v[170:173], v[140:143]
	v_mfma_f32_16x16x32_bf16 v[136:139], v[128:131], v[170:173], v[136:139]
	v_mfma_f32_16x16x32_bf16 v[76:79], v[120:123], v[178:181], v[76:79]
	v_mfma_f32_16x16x32_bf16 v[72:75], v[128:131], v[178:181], v[72:75]
	v_mfma_f32_16x16x32_bf16 v[88:91], v[120:123], v[186:189], v[88:91]
	v_mfma_f32_16x16x32_bf16 v[92:95], v[128:131], v[186:189], v[92:95]
	v_mfma_f32_16x16x32_bf16 v[96:99], v[120:123], v[194:197], v[96:99]
	v_mfma_f32_16x16x32_bf16 v[100:103], v[128:131], v[194:197], v[100:103]
	v_mfma_f32_16x16x32_bf16 v[140:143], v[124:127], v[174:177], v[140:143]
	v_mfma_f32_16x16x32_bf16 v[136:139], v[132:135], v[174:177], v[136:139]
	v_mfma_f32_16x16x32_bf16 v[76:79], v[124:127], v[182:185], v[76:79]
	v_mfma_f32_16x16x32_bf16 v[72:75], v[132:135], v[182:185], v[72:75]
	v_mfma_f32_16x16x32_bf16 v[88:91], v[124:127], v[190:193], v[88:91]
	v_mfma_f32_16x16x32_bf16 v[92:95], v[132:135], v[190:193], v[92:95]
	v_mfma_f32_16x16x32_bf16 v[96:99], v[124:127], v[202:205], v[96:99]
	v_mfma_f32_16x16x32_bf16 v[100:103], v[132:135], v[202:205], v[100:103]
	v_mfma_f32_16x16x32_bf16 v[60:63], v[144:147], v[170:173], v[60:63]
	v_mfma_f32_16x16x32_bf16 v[56:59], v[152:155], v[170:173], v[56:59]
	v_mfma_f32_16x16x32_bf16 v[52:55], v[144:147], v[178:181], v[52:55]
	v_mfma_f32_16x16x32_bf16 v[48:51], v[152:155], v[178:181], v[48:51]
	v_mfma_f32_16x16x32_bf16 v[44:47], v[144:147], v[186:189], v[44:47]
	v_mfma_f32_16x16x32_bf16 v[40:43], v[152:155], v[186:189], v[40:43]
	v_mfma_f32_16x16x32_bf16 v[36:39], v[144:147], v[194:197], v[36:39]
	v_mfma_f32_16x16x32_bf16 v[32:35], v[152:155], v[194:197], v[32:35]
	v_mfma_f32_16x16x32_bf16 v[60:63], v[148:151], v[174:177], v[60:63]
	v_mfma_f32_16x16x32_bf16 v[56:59], v[156:159], v[174:177], v[56:59]
	v_mfma_f32_16x16x32_bf16 v[52:55], v[148:151], v[182:185], v[52:55]
	v_mfma_f32_16x16x32_bf16 v[48:51], v[156:159], v[182:185], v[48:51]
	v_mfma_f32_16x16x32_bf16 v[44:47], v[148:151], v[190:193], v[44:47]
	v_mfma_f32_16x16x32_bf16 v[40:43], v[156:159], v[190:193], v[40:43]
	v_mfma_f32_16x16x32_bf16 v[36:39], v[148:151], v[202:205], v[36:39]
	v_mfma_f32_16x16x32_bf16 v[32:35], v[156:159], v[202:205], v[32:35]
	s_barrier
	s_add_i32 s74, s87, s33
	v_lshl_add_u64 v[198:199], v[198:199], 0, s[20:21]
	s_mov_b32 m0, s74
	ds_read_b128 v[170:173], v213 offset:49152
	ds_read_b128 v[174:177], v213 offset:50176
	ds_read_b128 v[178:181], v213 offset:51200
	ds_read_b128 v[182:185], v213 offset:52224
	ds_read_b128 v[186:189], v213 offset:53248
	ds_read_b128 v[190:193], v213 offset:54272
	ds_read_b128 v[194:197], v213 offset:55296
	ds_read_b128 v[202:205], v213 offset:56320
	global_load_lds_dwordx4 v[198:199], off
	s_add_i32 m0, s74, 0x2000
	s_add_u32 s52, s52, 0x80080
	v_lshl_add_u64 v[198:199], v[206:207], 0, s[20:21]
	s_addc_u32 s53, s53, 0
	s_add_i32 s74, s92, s33
	global_load_lds_dwordx4 v[198:199], off
	v_lshl_add_u64 v[198:199], s[52:53], 0, v[200:201]
	s_mov_b32 m0, s74
	s_nop 0
	global_load_lds_dwordx4 v[198:199], off
	v_lshl_add_u64 v[198:199], s[52:53], 0, v[160:161]
	s_add_i32 m0, s74, 0x2000
	s_nop 0
	global_load_lds_dwordx4 v[198:199], off
	v_lshl_add_u64 v[198:199], v[214:215], 0, s[20:21]
	s_mov_b32 m0, s85
	s_nop 0
	global_load_lds_dwordx4 v[198:199], off
	v_lshl_add_u64 v[198:199], v[216:217], 0, s[20:21]
	s_mov_b32 m0, s88
	s_nop 0
	global_load_lds_dwordx4 v[198:199], off
	s_waitcnt vmcnt(8)
	s_waitcnt lgkmcnt(0)
	s_barrier
	s_waitcnt lgkmcnt(0)
	v_mfma_f32_16x16x32_bf16 v[112:115], v[120:123], v[170:173], v[112:115]
	v_mfma_f32_16x16x32_bf16 v[104:107], v[128:131], v[170:173], v[104:107]
	v_mfma_f32_16x16x32_bf16 v[116:119], v[120:123], v[178:181], v[116:119]
	v_mfma_f32_16x16x32_bf16 v[108:111], v[128:131], v[178:181], v[108:111]
	v_mfma_f32_16x16x32_bf16 v[84:87], v[120:123], v[186:189], v[84:87]
	v_mfma_f32_16x16x32_bf16 v[80:83], v[128:131], v[186:189], v[80:83]
	v_mfma_f32_16x16x32_bf16 v[68:71], v[120:123], v[194:197], v[68:71]
	v_mfma_f32_16x16x32_bf16 v[64:67], v[128:131], v[194:197], v[64:67]
	v_mfma_f32_16x16x32_bf16 v[112:115], v[124:127], v[174:177], v[112:115]
	v_mfma_f32_16x16x32_bf16 v[104:107], v[132:135], v[174:177], v[104:107]
	v_mfma_f32_16x16x32_bf16 v[116:119], v[124:127], v[182:185], v[116:119]
	v_mfma_f32_16x16x32_bf16 v[108:111], v[132:135], v[182:185], v[108:111]
	v_mfma_f32_16x16x32_bf16 v[84:87], v[124:127], v[190:193], v[84:87]
	v_mfma_f32_16x16x32_bf16 v[80:83], v[132:135], v[190:193], v[80:83]
	v_mfma_f32_16x16x32_bf16 v[68:71], v[124:127], v[202:205], v[68:71]
	v_mfma_f32_16x16x32_bf16 v[64:67], v[132:135], v[202:205], v[64:67]
	v_mfma_f32_16x16x32_bf16 v[28:31], v[144:147], v[170:173], v[28:31]
	v_mfma_f32_16x16x32_bf16 v[24:27], v[152:155], v[170:173], v[24:27]
	v_mfma_f32_16x16x32_bf16 v[20:23], v[144:147], v[178:181], v[20:23]
	v_mfma_f32_16x16x32_bf16 v[16:19], v[152:155], v[178:181], v[16:19]
	v_mfma_f32_16x16x32_bf16 v[12:15], v[144:147], v[186:189], v[12:15]
	v_mfma_f32_16x16x32_bf16 v[8:11], v[152:155], v[186:189], v[8:11]
	v_mfma_f32_16x16x32_bf16 v[4:7], v[144:147], v[194:197], v[4:7]
	v_mfma_f32_16x16x32_bf16 v[0:3], v[152:155], v[194:197], v[0:3]
	v_mfma_f32_16x16x32_bf16 v[28:31], v[148:151], v[174:177], v[28:31]
	v_mfma_f32_16x16x32_bf16 v[24:27], v[156:159], v[174:177], v[24:27]
	v_mfma_f32_16x16x32_bf16 v[20:23], v[148:151], v[182:185], v[20:23]
	v_mfma_f32_16x16x32_bf16 v[16:19], v[156:159], v[182:185], v[16:19]
	v_mfma_f32_16x16x32_bf16 v[12:15], v[148:151], v[190:193], v[12:15]
	v_mfma_f32_16x16x32_bf16 v[8:11], v[156:159], v[190:193], v[8:11]
	v_mfma_f32_16x16x32_bf16 v[4:7], v[148:151], v[202:205], v[4:7]
	v_mfma_f32_16x16x32_bf16 v[0:3], v[156:159], v[202:205], v[0:3]
	s_barrier
	s_add_i32 s86, s86, 2
	s_add_u32 s76, s76, 0x100
	s_addc_u32 s77, s77, 0
	s_add_u32 s51, s51, 0x100
	s_addc_u32 s73, s73, 0
	s_cmp_gt_u32 s86, 29
	s_cbranch_scc0 .LBB0_768
	s_and_b64 vcc, exec, s[22:23]
	s_cbranch_vccz .LBB0_771
	s_barrier

.LBB0_860:
	s_add_u32 s52, s8, 0xfffc0080
	s_addc_u32 s53, s9, -1
	s_add_i32 s81, 0, 0x10000
	s_cmp_eq_u32 s80, 12
	s_cselect_b32 s75, s16, s53
	s_cselect_b32 s74, s17, s52
	s_cselect_b32 s53, s19, s79
	s_cselect_b32 s52, s23, s78
	s_add_i32 s84, 0, 0x14000
	v_add_u32_e32 v116, s81, v165
	v_add_u32_e32 v162, s84, v165
	ds_read_b128 v[104:107], v116
	ds_read_b128 v[108:111], v116 offset:1024
	ds_read_b128 v[112:115], v116 offset:2048
	ds_read_b128 v[116:119], v116 offset:3072
	ds_read_b128 v[154:157], v162
	ds_read_b128 v[158:161], v162 offset:1024
	ds_read_b128 v[168:171], v162 offset:2048
	ds_read_b128 v[172:175], v162 offset:3072
	v_lshl_add_u64 v[162:163], s[8:9], 0, v[150:151]
	s_add_i32 m0, s37, 0xc000
	ds_read_b128 v[176:179], v167
	ds_read_b128 v[180:183], v167 offset:1024
	ds_read_b128 v[184:187], v167 offset:2048
	ds_read_b128 v[188:191], v167 offset:3072
	ds_read_b128 v[192:195], v167 offset:4096
	ds_read_b128 v[196:199], v167 offset:5120
	ds_read_b128 v[206:209], v167 offset:6144
	ds_read_b128 v[210:213], v167 offset:7168
	global_load_lds_dwordx4 v[162:163], off
	v_lshl_add_u64 v[162:163], s[8:9], 0, v[152:153]
	s_add_i32 m0, s37, 0xe000
	s_nop 0
	global_load_lds_dwordx4 v[162:163], off
	s_waitcnt vmcnt(8)
	s_waitcnt lgkmcnt(0)
	s_barrier
	s_waitcnt lgkmcnt(0)
	v_mfma_f32_16x16x32_bf16 v[140:143], v[104:107], v[176:179], v[140:143]
	v_mfma_f32_16x16x32_bf16 v[136:139], v[112:115], v[176:179], v[136:139]
	v_mfma_f32_16x16x32_bf16 v[124:127], v[104:107], v[184:187], v[124:127]
	v_mfma_f32_16x16x32_bf16 v[120:123], v[112:115], v[184:187], v[120:123]
	v_mfma_f32_16x16x32_bf16 v[92:95], v[104:107], v[192:195], v[92:95]
	v_mfma_f32_16x16x32_bf16 v[88:91], v[112:115], v[192:195], v[88:91]
	v_mfma_f32_16x16x32_bf16 v[76:79], v[104:107], v[206:209], v[76:79]
	v_mfma_f32_16x16x32_bf16 v[72:75], v[112:115], v[206:209], v[72:75]
	v_mfma_f32_16x16x32_bf16 v[140:143], v[108:111], v[180:183], v[140:143]
	v_mfma_f32_16x16x32_bf16 v[136:139], v[116:119], v[180:183], v[136:139]
	v_mfma_f32_16x16x32_bf16 v[124:127], v[108:111], v[188:191], v[124:127]
	v_mfma_f32_16x16x32_bf16 v[120:123], v[116:119], v[188:191], v[120:123]
	v_mfma_f32_16x16x32_bf16 v[92:95], v[108:111], v[196:199], v[92:95]
	v_mfma_f32_16x16x32_bf16 v[88:91], v[116:119], v[196:199], v[88:91]
	v_mfma_f32_16x16x32_bf16 v[76:79], v[108:111], v[210:213], v[76:79]
	v_mfma_f32_16x16x32_bf16 v[72:75], v[116:119], v[210:213], v[72:75]
	v_mfma_f32_16x16x32_bf16 v[132:135], v[154:157], v[176:179], v[132:135]
	v_mfma_f32_16x16x32_bf16 v[128:131], v[168:171], v[176:179], v[128:131]
	v_mfma_f32_16x16x32_bf16 v[100:103], v[154:157], v[184:187], v[100:103]
	v_mfma_f32_16x16x32_bf16 v[96:99], v[168:171], v[184:187], v[96:99]
	v_mfma_f32_16x16x32_bf16 v[84:87], v[154:157], v[192:195], v[84:87]
	v_mfma_f32_16x16x32_bf16 v[80:83], v[168:171], v[192:195], v[80:83]
	v_mfma_f32_16x16x32_bf16 v[68:71], v[154:157], v[206:209], v[68:71]
	v_mfma_f32_16x16x32_bf16 v[64:67], v[168:171], v[206:209], v[64:67]
	v_mfma_f32_16x16x32_bf16 v[132:135], v[158:161], v[180:183], v[132:135]
	v_mfma_f32_16x16x32_bf16 v[128:131], v[172:175], v[180:183], v[128:131]
	v_mfma_f32_16x16x32_bf16 v[100:103], v[158:161], v[188:191], v[100:103]
	v_mfma_f32_16x16x32_bf16 v[96:99], v[172:175], v[188:191], v[96:99]
	v_mfma_f32_16x16x32_bf16 v[84:87], v[158:161], v[196:199], v[84:87]
	v_mfma_f32_16x16x32_bf16 v[80:83], v[172:175], v[196:199], v[80:83]
	v_mfma_f32_16x16x32_bf16 v[68:71], v[158:161], v[210:213], v[68:71]
	v_mfma_f32_16x16x32_bf16 v[64:67], v[172:175], v[210:213], v[64:67]
	s_barrier
	s_add_i32 s81, s81, s36
	v_lshl_add_u64 v[162:163], s[52:53], 0, v[200:201]
	s_mov_b32 m0, s81
	ds_read_b128 v[176:179], v167 offset:16384
	ds_read_b128 v[180:183], v167 offset:17408
	ds_read_b128 v[184:187], v167 offset:18432
	ds_read_b128 v[188:191], v167 offset:19456
	ds_read_b128 v[192:195], v167 offset:20480
	ds_read_b128 v[196:199], v167 offset:21504
	ds_read_b128 v[206:209], v167 offset:22528
	ds_read_b128 v[210:213], v167 offset:23552
	global_load_lds_dwordx4 v[162:163], off
	s_add_i32 m0, s81, 0x2000
	s_add_u32 s82, s52, 0x40000
	v_lshl_add_u64 v[202:203], s[52:53], 0, v[144:145]
	s_addc_u32 s83, s53, 0
	s_add_i32 s81, s84, s36
	global_load_lds_dwordx4 v[202:203], off
	v_lshl_add_u64 v[204:205], s[82:83], 0, v[200:201]
	s_mov_b32 m0, s81
	v_lshl_add_u64 v[214:215], s[74:75], 0, v[146:147]
	global_load_lds_dwordx4 v[204:205], off
	v_lshl_add_u64 v[204:205], s[82:83], 0, v[144:145]
	s_add_i32 m0, s81, 0x2000
	s_nop 0
	global_load_lds_dwordx4 v[204:205], off
	v_lshl_add_u64 v[204:205], s[74:75], 0, v[148:149]
	s_mov_b32 m0, s37
	s_nop 0
	global_load_lds_dwordx4 v[204:205], off
	s_mov_b32 m0, s38
	s_nop 0
	global_load_lds_dwordx4 v[214:215], off
	s_waitcnt vmcnt(8)
	s_waitcnt lgkmcnt(0)
	s_barrier
	s_waitcnt lgkmcnt(0)
	v_mfma_f32_16x16x32_bf16 v[60:63], v[104:107], v[176:179], v[60:63]
	v_mfma_f32_16x16x32_bf16 v[56:59], v[112:115], v[176:179], v[56:59]
	v_mfma_f32_16x16x32_bf16 v[44:47], v[104:107], v[184:187], v[44:47]
	v_mfma_f32_16x16x32_bf16 v[40:43], v[112:115], v[184:187], v[40:43]
	v_mfma_f32_16x16x32_bf16 v[28:31], v[104:107], v[192:195], v[28:31]
	v_mfma_f32_16x16x32_bf16 v[24:27], v[112:115], v[192:195], v[24:27]
	v_mfma_f32_16x16x32_bf16 v[12:15], v[104:107], v[206:209], v[12:15]
	v_mfma_f32_16x16x32_bf16 v[8:11], v[112:115], v[206:209], v[8:11]
	v_mfma_f32_16x16x32_bf16 v[60:63], v[108:111], v[180:183], v[60:63]
	v_mfma_f32_16x16x32_bf16 v[56:59], v[116:119], v[180:183], v[56:59]
	v_mfma_f32_16x16x32_bf16 v[44:47], v[108:111], v[188:191], v[44:47]
	v_mfma_f32_16x16x32_bf16 v[40:43], v[116:119], v[188:191], v[40:43]
	v_mfma_f32_16x16x32_bf16 v[28:31], v[108:111], v[196:199], v[28:31]
	v_mfma_f32_16x16x32_bf16 v[24:27], v[116:119], v[196:199], v[24:27]
	v_mfma_f32_16x16x32_bf16 v[12:15], v[108:111], v[210:213], v[12:15]
	v_mfma_f32_16x16x32_bf16 v[8:11], v[116:119], v[210:213], v[8:11]
	v_mfma_f32_16x16x32_bf16 v[52:55], v[154:157], v[176:179], v[52:55]
	v_mfma_f32_16x16x32_bf16 v[48:51], v[168:171], v[176:179], v[48:51]
	v_mfma_f32_16x16x32_bf16 v[36:39], v[154:157], v[184:187], v[36:39]
	v_mfma_f32_16x16x32_bf16 v[32:35], v[168:171], v[184:187], v[32:35]
	v_mfma_f32_16x16x32_bf16 v[20:23], v[154:157], v[192:195], v[20:23]
	v_mfma_f32_16x16x32_bf16 v[16:19], v[168:171], v[192:195], v[16:19]
	v_mfma_f32_16x16x32_bf16 v[4:7], v[154:157], v[206:209], v[4:7]
	v_mfma_f32_16x16x32_bf16 v[0:3], v[168:171], v[206:209], v[0:3]
	v_mfma_f32_16x16x32_bf16 v[52:55], v[158:161], v[180:183], v[52:55]
	v_mfma_f32_16x16x32_bf16 v[48:51], v[172:175], v[180:183], v[48:51]
	v_mfma_f32_16x16x32_bf16 v[36:39], v[158:161], v[188:191], v[36:39]
	v_mfma_f32_16x16x32_bf16 v[32:35], v[172:175], v[188:191], v[32:35]
	v_mfma_f32_16x16x32_bf16 v[20:23], v[158:161], v[196:199], v[20:23]
	v_mfma_f32_16x16x32_bf16 v[16:19], v[172:175], v[196:199], v[16:19]
	v_mfma_f32_16x16x32_bf16 v[4:7], v[158:161], v[210:213], v[4:7]
	v_mfma_f32_16x16x32_bf16 v[0:3], v[172:175], v[210:213], v[0:3]
	s_barrier
	s_add_i32 s81, 0, 0x18000
	s_add_i32 s82, 0, 0x1c000
	v_add_u32_e32 v116, s81, v165
	v_add_u32_e32 v172, s82, v165
	ds_read_b128 v[104:107], v116
	ds_read_b128 v[108:111], v116 offset:1024
	ds_read_b128 v[112:115], v116 offset:2048
	ds_read_b128 v[116:119], v116 offset:3072
	ds_read_b128 v[154:157], v172
	ds_read_b128 v[158:161], v172 offset:1024
	ds_read_b128 v[168:171], v172 offset:2048
	ds_read_b128 v[172:175], v172 offset:3072
	s_add_u32 s74, s74, 0x40000
	s_addc_u32 s75, s75, 0
	s_mov_b32 m0, s39
	v_lshl_add_u64 v[216:217], s[74:75], 0, v[148:149]
	ds_read_b128 v[176:179], v167 offset:32768
	ds_read_b128 v[180:183], v167 offset:33792
	ds_read_b128 v[184:187], v167 offset:34816
	ds_read_b128 v[188:191], v167 offset:35840
	ds_read_b128 v[192:195], v167 offset:36864
	ds_read_b128 v[196:199], v167 offset:37888
	ds_read_b128 v[206:209], v167 offset:38912
	ds_read_b128 v[210:213], v167 offset:39936
	global_load_lds_dwordx4 v[216:217], off
	v_lshl_add_u64 v[216:217], s[74:75], 0, v[146:147]
	s_mov_b32 m0, s50
	s_nop 0
	global_load_lds_dwordx4 v[216:217], off
	s_waitcnt vmcnt(8)
	s_waitcnt lgkmcnt(0)
	s_barrier
	s_waitcnt lgkmcnt(0)
	v_mfma_f32_16x16x32_bf16 v[140:143], v[104:107], v[176:179], v[140:143]
	v_mfma_f32_16x16x32_bf16 v[136:139], v[112:115], v[176:179], v[136:139]
	v_mfma_f32_16x16x32_bf16 v[124:127], v[104:107], v[184:187], v[124:127]
	v_mfma_f32_16x16x32_bf16 v[120:123], v[112:115], v[184:187], v[120:123]
	v_mfma_f32_16x16x32_bf16 v[92:95], v[104:107], v[192:195], v[92:95]
	v_mfma_f32_16x16x32_bf16 v[88:91], v[112:115], v[192:195], v[88:91]
	v_mfma_f32_16x16x32_bf16 v[76:79], v[104:107], v[206:209], v[76:79]
	v_mfma_f32_16x16x32_bf16 v[72:75], v[112:115], v[206:209], v[72:75]
	v_mfma_f32_16x16x32_bf16 v[140:143], v[108:111], v[180:183], v[140:143]
	v_mfma_f32_16x16x32_bf16 v[136:139], v[116:119], v[180:183], v[136:139]
	v_mfma_f32_16x16x32_bf16 v[124:127], v[108:111], v[188:191], v[124:127]
	v_mfma_f32_16x16x32_bf16 v[120:123], v[116:119], v[188:191], v[120:123]
	v_mfma_f32_16x16x32_bf16 v[92:95], v[108:111], v[196:199], v[92:95]
	v_mfma_f32_16x16x32_bf16 v[88:91], v[116:119], v[196:199], v[88:91]
	v_mfma_f32_16x16x32_bf16 v[76:79], v[108:111], v[210:213], v[76:79]
	v_mfma_f32_16x16x32_bf16 v[72:75], v[116:119], v[210:213], v[72:75]
	v_mfma_f32_16x16x32_bf16 v[132:135], v[154:157], v[176:179], v[132:135]
	v_mfma_f32_16x16x32_bf16 v[128:131], v[168:171], v[176:179], v[128:131]
	v_mfma_f32_16x16x32_bf16 v[100:103], v[154:157], v[184:187], v[100:103]
	v_mfma_f32_16x16x32_bf16 v[96:99], v[168:171], v[184:187], v[96:99]
	v_mfma_f32_16x16x32_bf16 v[84:87], v[154:157], v[192:195], v[84:87]
	v_mfma_f32_16x16x32_bf16 v[80:83], v[168:171], v[192:195], v[80:83]
	v_mfma_f32_16x16x32_bf16 v[68:71], v[154:157], v[206:209], v[68:71]
	v_mfma_f32_16x16x32_bf16 v[64:67], v[168:171], v[206:209], v[64:67]
	v_mfma_f32_16x16x32_bf16 v[132:135], v[158:161], v[180:183], v[132:135]
	v_mfma_f32_16x16x32_bf16 v[128:131], v[172:175], v[180:183], v[128:131]
	v_mfma_f32_16x16x32_bf16 v[100:103], v[158:161], v[188:191], v[100:103]
	v_mfma_f32_16x16x32_bf16 v[96:99], v[172:175], v[188:191], v[96:99]
	v_mfma_f32_16x16x32_bf16 v[84:87], v[158:161], v[196:199], v[84:87]
	v_mfma_f32_16x16x32_bf16 v[80:83], v[172:175], v[196:199], v[80:83]
	v_mfma_f32_16x16x32_bf16 v[68:71], v[158:161], v[210:213], v[68:71]
	v_mfma_f32_16x16x32_bf16 v[64:67], v[172:175], v[210:213], v[64:67]
	s_barrier
	s_add_i32 s74, s81, s36
	v_lshl_add_u64 v[162:163], v[162:163], 0, s[20:21]
	s_mov_b32 m0, s74
	ds_read_b128 v[176:179], v167 offset:49152
	ds_read_b128 v[180:183], v167 offset:50176
	ds_read_b128 v[184:187], v167 offset:51200
	ds_read_b128 v[188:191], v167 offset:52224
	ds_read_b128 v[192:195], v167 offset:53248
	ds_read_b128 v[196:199], v167 offset:54272
	ds_read_b128 v[206:209], v167 offset:55296
	ds_read_b128 v[210:213], v167 offset:56320
	global_load_lds_dwordx4 v[162:163], off
	s_add_i32 m0, s74, 0x2000
	s_add_u32 s52, s52, 0x40080
	v_lshl_add_u64 v[162:163], v[202:203], 0, s[20:21]
	s_addc_u32 s53, s53, 0
	s_add_i32 s74, s82, s36
	global_load_lds_dwordx4 v[162:163], off
	v_lshl_add_u64 v[162:163], s[52:53], 0, v[200:201]
	s_mov_b32 m0, s74
	s_nop 0
	global_load_lds_dwordx4 v[162:163], off
	v_lshl_add_u64 v[162:163], s[52:53], 0, v[144:145]
	s_add_i32 m0, s74, 0x2000
	s_nop 0
	global_load_lds_dwordx4 v[162:163], off
	v_lshl_add_u64 v[162:163], v[204:205], 0, s[20:21]
	s_mov_b32 m0, s51
	s_nop 0
	global_load_lds_dwordx4 v[162:163], off
	v_lshl_add_u64 v[162:163], v[214:215], 0, s[20:21]
	s_mov_b32 m0, s76
	s_nop 0
	global_load_lds_dwordx4 v[162:163], off
	s_waitcnt vmcnt(8)
	s_waitcnt lgkmcnt(0)
	s_barrier
	s_waitcnt lgkmcnt(0)
	v_mfma_f32_16x16x32_bf16 v[60:63], v[104:107], v[176:179], v[60:63]
	v_mfma_f32_16x16x32_bf16 v[56:59], v[112:115], v[176:179], v[56:59]
	v_mfma_f32_16x16x32_bf16 v[44:47], v[104:107], v[184:187], v[44:47]
	v_mfma_f32_16x16x32_bf16 v[40:43], v[112:115], v[184:187], v[40:43]
	v_mfma_f32_16x16x32_bf16 v[28:31], v[104:107], v[192:195], v[28:31]
	v_mfma_f32_16x16x32_bf16 v[24:27], v[112:115], v[192:195], v[24:27]
	v_mfma_f32_16x16x32_bf16 v[12:15], v[104:107], v[206:209], v[12:15]
	v_mfma_f32_16x16x32_bf16 v[8:11], v[112:115], v[206:209], v[8:11]
	v_mfma_f32_16x16x32_bf16 v[60:63], v[108:111], v[180:183], v[60:63]
	v_mfma_f32_16x16x32_bf16 v[56:59], v[116:119], v[180:183], v[56:59]
	v_mfma_f32_16x16x32_bf16 v[44:47], v[108:111], v[188:191], v[44:47]
	v_mfma_f32_16x16x32_bf16 v[40:43], v[116:119], v[188:191], v[40:43]
	v_mfma_f32_16x16x32_bf16 v[28:31], v[108:111], v[196:199], v[28:31]
	v_mfma_f32_16x16x32_bf16 v[24:27], v[116:119], v[196:199], v[24:27]
	v_mfma_f32_16x16x32_bf16 v[12:15], v[108:111], v[210:213], v[12:15]
	v_mfma_f32_16x16x32_bf16 v[8:11], v[116:119], v[210:213], v[8:11]
	v_mfma_f32_16x16x32_bf16 v[52:55], v[154:157], v[176:179], v[52:55]
	v_mfma_f32_16x16x32_bf16 v[48:51], v[168:171], v[176:179], v[48:51]
	v_mfma_f32_16x16x32_bf16 v[36:39], v[154:157], v[184:187], v[36:39]
	v_mfma_f32_16x16x32_bf16 v[32:35], v[168:171], v[184:187], v[32:35]
	v_mfma_f32_16x16x32_bf16 v[20:23], v[154:157], v[192:195], v[20:23]
	v_mfma_f32_16x16x32_bf16 v[16:19], v[168:171], v[192:195], v[16:19]
	v_mfma_f32_16x16x32_bf16 v[4:7], v[154:157], v[206:209], v[4:7]
	v_mfma_f32_16x16x32_bf16 v[0:3], v[168:171], v[206:209], v[0:3]
	v_mfma_f32_16x16x32_bf16 v[52:55], v[158:161], v[180:183], v[52:55]
	v_mfma_f32_16x16x32_bf16 v[48:51], v[172:175], v[180:183], v[48:51]
	v_mfma_f32_16x16x32_bf16 v[36:39], v[158:161], v[188:191], v[36:39]
	v_mfma_f32_16x16x32_bf16 v[32:35], v[172:175], v[188:191], v[32:35]
	v_mfma_f32_16x16x32_bf16 v[20:23], v[158:161], v[196:199], v[20:23]
	v_mfma_f32_16x16x32_bf16 v[16:19], v[172:175], v[196:199], v[16:19]
	v_mfma_f32_16x16x32_bf16 v[4:7], v[158:161], v[210:213], v[4:7]
	v_mfma_f32_16x16x32_bf16 v[0:3], v[172:175], v[210:213], v[0:3]
	s_barrier
	s_add_i32 s80, s80, 2
	s_add_u32 s8, s8, 0x100
	s_addc_u32 s9, s9, 0
	s_add_u32 s78, s78, 0x100
	s_addc_u32 s79, s79, 0
	s_cmp_gt_u32 s80, 13
	s_cbranch_scc0 .LBB0_860
	s_and_b64 vcc, exec, s[14:15]
	s_cbranch_vccz .LBB0_863
	s_barrier

.LBB0_1132:
	s_add_u32 s41, s76, 0xfffe0080
	s_addc_u32 s42, s77, -1
	s_add_i32 s43, 0, 0x10000
	s_cmp_eq_u32 s40, 4
	s_cselect_b32 s75, s16, s42
	s_cselect_b32 s74, s17, s41
	s_cselect_b32 s53, s23, s39
	s_cselect_b32 s52, s25, s38
	s_add_i32 s41, 0, 0x14000
	v_add_u32_e32 v140, s43, v183
	v_add_u32_e32 v166, s41, v183
	ds_read_b128 v[116:119], v140
	ds_read_b128 v[128:131], v140 offset:1024
	ds_read_b128 v[136:139], v140 offset:2048
	ds_read_b128 v[140:143], v140 offset:3072
	ds_read_b128 v[144:147], v166
	ds_read_b128 v[148:151], v166 offset:1024
	ds_read_b128 v[152:155], v166 offset:2048
	ds_read_b128 v[166:169], v166 offset:3072
	v_lshl_add_u64 v[198:199], s[76:77], 0, v[162:163]
	s_add_i32 m0, s34, 0xc000
	ds_read_b128 v[170:173], v185
	ds_read_b128 v[174:177], v185 offset:1024
	ds_read_b128 v[178:181], v185 offset:2048
	ds_read_b128 v[186:189], v185 offset:3072
	ds_read_b128 v[190:193], v185 offset:4096
	ds_read_b128 v[194:197], v185 offset:5120
	ds_read_b128 v[206:209], v185 offset:6144
	ds_read_b128 v[210:213], v185 offset:7168
	global_load_lds_dwordx4 v[198:199], off
	v_lshl_add_u64 v[198:199], s[76:77], 0, v[164:165]
	s_add_i32 m0, s34, 0xe000
	s_nop 0
	global_load_lds_dwordx4 v[198:199], off
	s_waitcnt vmcnt(8)
	s_waitcnt lgkmcnt(0)
	s_barrier
	s_waitcnt lgkmcnt(0)
	v_mfma_f32_16x16x32_bf16 v[132:135], v[116:119], v[170:173], v[132:135]
	v_mfma_f32_16x16x32_bf16 v[112:115], v[136:139], v[170:173], v[112:115]
	v_mfma_f32_16x16x32_bf16 v[108:111], v[116:119], v[178:181], v[108:111]
	v_mfma_f32_16x16x32_bf16 v[104:107], v[136:139], v[178:181], v[104:107]
	v_mfma_f32_16x16x32_bf16 v[92:95], v[116:119], v[190:193], v[92:95]
	v_mfma_f32_16x16x32_bf16 v[88:91], v[136:139], v[190:193], v[88:91]
	v_mfma_f32_16x16x32_bf16 v[76:79], v[116:119], v[206:209], v[76:79]
	v_mfma_f32_16x16x32_bf16 v[72:75], v[136:139], v[206:209], v[72:75]
	v_mfma_f32_16x16x32_bf16 v[132:135], v[128:131], v[174:177], v[132:135]
	v_mfma_f32_16x16x32_bf16 v[112:115], v[140:143], v[174:177], v[112:115]
	v_mfma_f32_16x16x32_bf16 v[108:111], v[128:131], v[186:189], v[108:111]
	v_mfma_f32_16x16x32_bf16 v[104:107], v[140:143], v[186:189], v[104:107]
	v_mfma_f32_16x16x32_bf16 v[92:95], v[128:131], v[194:197], v[92:95]
	v_mfma_f32_16x16x32_bf16 v[88:91], v[140:143], v[194:197], v[88:91]
	v_mfma_f32_16x16x32_bf16 v[76:79], v[128:131], v[210:213], v[76:79]
	v_mfma_f32_16x16x32_bf16 v[72:75], v[140:143], v[210:213], v[72:75]
	v_mfma_f32_16x16x32_bf16 v[124:127], v[144:147], v[170:173], v[124:127]
	v_mfma_f32_16x16x32_bf16 v[120:123], v[152:155], v[170:173], v[120:123]
	v_mfma_f32_16x16x32_bf16 v[100:103], v[144:147], v[178:181], v[100:103]
	v_mfma_f32_16x16x32_bf16 v[96:99], v[152:155], v[178:181], v[96:99]
	v_mfma_f32_16x16x32_bf16 v[84:87], v[144:147], v[190:193], v[84:87]
	v_mfma_f32_16x16x32_bf16 v[80:83], v[152:155], v[190:193], v[80:83]
	v_mfma_f32_16x16x32_bf16 v[68:71], v[144:147], v[206:209], v[68:71]
	v_mfma_f32_16x16x32_bf16 v[64:67], v[152:155], v[206:209], v[64:67]
	v_mfma_f32_16x16x32_bf16 v[124:127], v[148:151], v[174:177], v[124:127]
	v_mfma_f32_16x16x32_bf16 v[120:123], v[166:169], v[174:177], v[120:123]
	v_mfma_f32_16x16x32_bf16 v[100:103], v[148:151], v[186:189], v[100:103]
	v_mfma_f32_16x16x32_bf16 v[96:99], v[166:169], v[186:189], v[96:99]
	v_mfma_f32_16x16x32_bf16 v[84:87], v[148:151], v[194:197], v[84:87]
	v_mfma_f32_16x16x32_bf16 v[80:83], v[166:169], v[194:197], v[80:83]
	v_mfma_f32_16x16x32_bf16 v[68:71], v[148:151], v[210:213], v[68:71]
	v_mfma_f32_16x16x32_bf16 v[64:67], v[166:169], v[210:213], v[64:67]
	s_barrier
	s_add_i32 s42, s43, s33
	v_lshl_add_u64 v[198:199], s[52:53], 0, v[200:201]
	s_mov_b32 m0, s42
	ds_read_b128 v[170:173], v185 offset:16384
	ds_read_b128 v[174:177], v185 offset:17408
	ds_read_b128 v[178:181], v185 offset:18432
	ds_read_b128 v[186:189], v185 offset:19456
	ds_read_b128 v[190:193], v185 offset:20480
	ds_read_b128 v[194:197], v185 offset:21504
	ds_read_b128 v[206:209], v185 offset:22528
	ds_read_b128 v[210:213], v185 offset:23552
	global_load_lds_dwordx4 v[198:199], off
	s_add_i32 m0, s42, 0x2000
	s_add_u32 s42, s52, 0x20000
	v_lshl_add_u64 v[202:203], s[52:53], 0, v[156:157]
	s_addc_u32 s43, s53, 0
	s_add_i32 s41, s41, s33
	global_load_lds_dwordx4 v[202:203], off
	v_lshl_add_u64 v[204:205], s[42:43], 0, v[200:201]
	s_mov_b32 m0, s41
	v_lshl_add_u64 v[214:215], s[74:75], 0, v[158:159]
	global_load_lds_dwordx4 v[204:205], off
	v_lshl_add_u64 v[204:205], s[42:43], 0, v[156:157]
	s_add_i32 m0, s41, 0x2000
	s_nop 0
	global_load_lds_dwordx4 v[204:205], off
	v_lshl_add_u64 v[204:205], s[74:75], 0, v[160:161]
	s_mov_b32 m0, s34
	s_nop 0
	global_load_lds_dwordx4 v[204:205], off
	s_mov_b32 m0, s50
	s_nop 0
	global_load_lds_dwordx4 v[214:215], off
	s_waitcnt vmcnt(8)
	s_waitcnt lgkmcnt(0)
	s_barrier
	s_waitcnt lgkmcnt(0)
	v_mfma_f32_16x16x32_bf16 v[60:63], v[116:119], v[170:173], v[60:63]
	v_mfma_f32_16x16x32_bf16 v[56:59], v[136:139], v[170:173], v[56:59]
	v_mfma_f32_16x16x32_bf16 v[44:47], v[116:119], v[178:181], v[44:47]
	v_mfma_f32_16x16x32_bf16 v[40:43], v[136:139], v[178:181], v[40:43]
	v_mfma_f32_16x16x32_bf16 v[28:31], v[116:119], v[190:193], v[28:31]
	v_mfma_f32_16x16x32_bf16 v[24:27], v[136:139], v[190:193], v[24:27]
	v_mfma_f32_16x16x32_bf16 v[12:15], v[116:119], v[206:209], v[12:15]
	v_mfma_f32_16x16x32_bf16 v[8:11], v[136:139], v[206:209], v[8:11]
	v_mfma_f32_16x16x32_bf16 v[60:63], v[128:131], v[174:177], v[60:63]
	v_mfma_f32_16x16x32_bf16 v[56:59], v[140:143], v[174:177], v[56:59]
	v_mfma_f32_16x16x32_bf16 v[44:47], v[128:131], v[186:189], v[44:47]
	v_mfma_f32_16x16x32_bf16 v[40:43], v[140:143], v[186:189], v[40:43]
	v_mfma_f32_16x16x32_bf16 v[28:31], v[128:131], v[194:197], v[28:31]
	v_mfma_f32_16x16x32_bf16 v[24:27], v[140:143], v[194:197], v[24:27]
	v_mfma_f32_16x16x32_bf16 v[12:15], v[128:131], v[210:213], v[12:15]
	v_mfma_f32_16x16x32_bf16 v[8:11], v[140:143], v[210:213], v[8:11]
	v_mfma_f32_16x16x32_bf16 v[52:55], v[144:147], v[170:173], v[52:55]
	v_mfma_f32_16x16x32_bf16 v[48:51], v[152:155], v[170:173], v[48:51]
	v_mfma_f32_16x16x32_bf16 v[36:39], v[144:147], v[178:181], v[36:39]
	v_mfma_f32_16x16x32_bf16 v[32:35], v[152:155], v[178:181], v[32:35]
	v_mfma_f32_16x16x32_bf16 v[20:23], v[144:147], v[190:193], v[20:23]
	v_mfma_f32_16x16x32_bf16 v[16:19], v[152:155], v[190:193], v[16:19]
	v_mfma_f32_16x16x32_bf16 v[4:7], v[144:147], v[206:209], v[4:7]
	v_mfma_f32_16x16x32_bf16 v[0:3], v[152:155], v[206:209], v[0:3]
	v_mfma_f32_16x16x32_bf16 v[52:55], v[148:151], v[174:177], v[52:55]
	v_mfma_f32_16x16x32_bf16 v[48:51], v[166:169], v[174:177], v[48:51]
	v_mfma_f32_16x16x32_bf16 v[36:39], v[148:151], v[186:189], v[36:39]
	v_mfma_f32_16x16x32_bf16 v[32:35], v[166:169], v[186:189], v[32:35]
	v_mfma_f32_16x16x32_bf16 v[20:23], v[148:151], v[194:197], v[20:23]
	v_mfma_f32_16x16x32_bf16 v[16:19], v[166:169], v[194:197], v[16:19]
	v_mfma_f32_16x16x32_bf16 v[4:7], v[148:151], v[210:213], v[4:7]
	v_mfma_f32_16x16x32_bf16 v[0:3], v[166:169], v[210:213], v[0:3]
	s_barrier
	s_add_i32 s41, 0, 0x18000
	s_add_i32 s84, 0, 0x1c000
	v_add_u32_e32 v140, s41, v183
	v_add_u32_e32 v166, s84, v183
	ds_read_b128 v[116:119], v140
	ds_read_b128 v[128:131], v140 offset:1024
	ds_read_b128 v[136:139], v140 offset:2048
	ds_read_b128 v[140:143], v140 offset:3072
	ds_read_b128 v[144:147], v166
	ds_read_b128 v[148:151], v166 offset:1024
	ds_read_b128 v[152:155], v166 offset:2048
	ds_read_b128 v[166:169], v166 offset:3072
	s_add_u32 s42, s74, 0x20000
	s_addc_u32 s43, s75, 0
	s_mov_b32 m0, s51
	v_lshl_add_u64 v[216:217], s[42:43], 0, v[160:161]
	ds_read_b128 v[170:173], v185 offset:32768
	ds_read_b128 v[174:177], v185 offset:33792
	ds_read_b128 v[178:181], v185 offset:34816
	ds_read_b128 v[186:189], v185 offset:35840
	ds_read_b128 v[190:193], v185 offset:36864
	ds_read_b128 v[194:197], v185 offset:37888
	ds_read_b128 v[206:209], v185 offset:38912
	ds_read_b128 v[210:213], v185 offset:39936
	global_load_lds_dwordx4 v[216:217], off
	v_lshl_add_u64 v[216:217], s[42:43], 0, v[158:159]
	s_mov_b32 m0, s80
	s_nop 0
	global_load_lds_dwordx4 v[216:217], off
	s_waitcnt vmcnt(8)
	s_waitcnt lgkmcnt(0)
	s_barrier
	s_waitcnt lgkmcnt(0)
	v_mfma_f32_16x16x32_bf16 v[132:135], v[116:119], v[170:173], v[132:135]
	v_mfma_f32_16x16x32_bf16 v[112:115], v[136:139], v[170:173], v[112:115]
	v_mfma_f32_16x16x32_bf16 v[108:111], v[116:119], v[178:181], v[108:111]
	v_mfma_f32_16x16x32_bf16 v[104:107], v[136:139], v[178:181], v[104:107]
	v_mfma_f32_16x16x32_bf16 v[92:95], v[116:119], v[190:193], v[92:95]
	v_mfma_f32_16x16x32_bf16 v[88:91], v[136:139], v[190:193], v[88:91]
	v_mfma_f32_16x16x32_bf16 v[76:79], v[116:119], v[206:209], v[76:79]
	v_mfma_f32_16x16x32_bf16 v[72:75], v[136:139], v[206:209], v[72:75]
	v_mfma_f32_16x16x32_bf16 v[132:135], v[128:131], v[174:177], v[132:135]
	v_mfma_f32_16x16x32_bf16 v[112:115], v[140:143], v[174:177], v[112:115]
	v_mfma_f32_16x16x32_bf16 v[108:111], v[128:131], v[186:189], v[108:111]
	v_mfma_f32_16x16x32_bf16 v[104:107], v[140:143], v[186:189], v[104:107]
	v_mfma_f32_16x16x32_bf16 v[92:95], v[128:131], v[194:197], v[92:95]
	v_mfma_f32_16x16x32_bf16 v[88:91], v[140:143], v[194:197], v[88:91]
	v_mfma_f32_16x16x32_bf16 v[76:79], v[128:131], v[210:213], v[76:79]
	v_mfma_f32_16x16x32_bf16 v[72:75], v[140:143], v[210:213], v[72:75]
	v_mfma_f32_16x16x32_bf16 v[124:127], v[144:147], v[170:173], v[124:127]
	v_mfma_f32_16x16x32_bf16 v[120:123], v[152:155], v[170:173], v[120:123]
	v_mfma_f32_16x16x32_bf16 v[100:103], v[144:147], v[178:181], v[100:103]
	v_mfma_f32_16x16x32_bf16 v[96:99], v[152:155], v[178:181], v[96:99]
	v_mfma_f32_16x16x32_bf16 v[84:87], v[144:147], v[190:193], v[84:87]
	v_mfma_f32_16x16x32_bf16 v[80:83], v[152:155], v[190:193], v[80:83]
	v_mfma_f32_16x16x32_bf16 v[68:71], v[144:147], v[206:209], v[68:71]
	v_mfma_f32_16x16x32_bf16 v[64:67], v[152:155], v[206:209], v[64:67]
	v_mfma_f32_16x16x32_bf16 v[124:127], v[148:151], v[174:177], v[124:127]
	v_mfma_f32_16x16x32_bf16 v[120:123], v[166:169], v[174:177], v[120:123]
	v_mfma_f32_16x16x32_bf16 v[100:103], v[148:151], v[186:189], v[100:103]
	v_mfma_f32_16x16x32_bf16 v[96:99], v[166:169], v[186:189], v[96:99]
	v_mfma_f32_16x16x32_bf16 v[84:87], v[148:151], v[194:197], v[84:87]
	v_mfma_f32_16x16x32_bf16 v[80:83], v[166:169], v[194:197], v[80:83]
	v_mfma_f32_16x16x32_bf16 v[68:71], v[148:151], v[210:213], v[68:71]
	v_mfma_f32_16x16x32_bf16 v[64:67], v[166:169], v[210:213], v[64:67]
	s_barrier
	s_add_i32 s41, s41, s33
	v_lshl_add_u64 v[198:199], v[198:199], 0, s[20:21]
	s_mov_b32 m0, s41
	ds_read_b128 v[170:173], v185 offset:49152
	ds_read_b128 v[174:177], v185 offset:50176
	ds_read_b128 v[178:181], v185 offset:51200
	ds_read_b128 v[186:189], v185 offset:52224
	ds_read_b128 v[190:193], v185 offset:53248
	ds_read_b128 v[194:197], v185 offset:54272
	ds_read_b128 v[206:209], v185 offset:55296
	ds_read_b128 v[210:213], v185 offset:56320
	global_load_lds_dwordx4 v[198:199], off
	s_add_i32 m0, s41, 0x2000
	s_add_u32 s42, s52, 0x20080
	v_lshl_add_u64 v[198:199], v[202:203], 0, s[20:21]
	s_addc_u32 s43, s53, 0
	s_add_i32 s41, s84, s33
	global_load_lds_dwordx4 v[198:199], off
	v_lshl_add_u64 v[198:199], s[42:43], 0, v[200:201]
	s_mov_b32 m0, s41
	s_nop 0
	global_load_lds_dwordx4 v[198:199], off
	v_lshl_add_u64 v[198:199], s[42:43], 0, v[156:157]
	s_add_i32 m0, s41, 0x2000
	s_nop 0
	global_load_lds_dwordx4 v[198:199], off
	v_lshl_add_u64 v[198:199], v[204:205], 0, s[20:21]
	s_mov_b32 m0, s81
	s_nop 0
	global_load_lds_dwordx4 v[198:199], off
	v_lshl_add_u64 v[198:199], v[214:215], 0, s[20:21]
	s_mov_b32 m0, s82
	s_nop 0
	global_load_lds_dwordx4 v[198:199], off
	s_waitcnt vmcnt(8)
	s_waitcnt lgkmcnt(0)
	s_barrier
	s_waitcnt lgkmcnt(0)
	v_mfma_f32_16x16x32_bf16 v[60:63], v[116:119], v[170:173], v[60:63]
	v_mfma_f32_16x16x32_bf16 v[56:59], v[136:139], v[170:173], v[56:59]
	v_mfma_f32_16x16x32_bf16 v[44:47], v[116:119], v[178:181], v[44:47]
	v_mfma_f32_16x16x32_bf16 v[40:43], v[136:139], v[178:181], v[40:43]
	v_mfma_f32_16x16x32_bf16 v[28:31], v[116:119], v[190:193], v[28:31]
	v_mfma_f32_16x16x32_bf16 v[24:27], v[136:139], v[190:193], v[24:27]
	v_mfma_f32_16x16x32_bf16 v[12:15], v[116:119], v[206:209], v[12:15]
	v_mfma_f32_16x16x32_bf16 v[8:11], v[136:139], v[206:209], v[8:11]
	v_mfma_f32_16x16x32_bf16 v[60:63], v[128:131], v[174:177], v[60:63]
	v_mfma_f32_16x16x32_bf16 v[56:59], v[140:143], v[174:177], v[56:59]
	v_mfma_f32_16x16x32_bf16 v[44:47], v[128:131], v[186:189], v[44:47]
	v_mfma_f32_16x16x32_bf16 v[40:43], v[140:143], v[186:189], v[40:43]
	v_mfma_f32_16x16x32_bf16 v[28:31], v[128:131], v[194:197], v[28:31]
	v_mfma_f32_16x16x32_bf16 v[24:27], v[140:143], v[194:197], v[24:27]
	v_mfma_f32_16x16x32_bf16 v[12:15], v[128:131], v[210:213], v[12:15]
	v_mfma_f32_16x16x32_bf16 v[8:11], v[140:143], v[210:213], v[8:11]
	v_mfma_f32_16x16x32_bf16 v[52:55], v[144:147], v[170:173], v[52:55]
	v_mfma_f32_16x16x32_bf16 v[48:51], v[152:155], v[170:173], v[48:51]
	v_mfma_f32_16x16x32_bf16 v[36:39], v[144:147], v[178:181], v[36:39]
	v_mfma_f32_16x16x32_bf16 v[32:35], v[152:155], v[178:181], v[32:35]
	v_mfma_f32_16x16x32_bf16 v[20:23], v[144:147], v[190:193], v[20:23]
	v_mfma_f32_16x16x32_bf16 v[16:19], v[152:155], v[190:193], v[16:19]
	v_mfma_f32_16x16x32_bf16 v[4:7], v[144:147], v[206:209], v[4:7]
	v_mfma_f32_16x16x32_bf16 v[0:3], v[152:155], v[206:209], v[0:3]
	v_mfma_f32_16x16x32_bf16 v[52:55], v[148:151], v[174:177], v[52:55]
	v_mfma_f32_16x16x32_bf16 v[48:51], v[166:169], v[174:177], v[48:51]
	v_mfma_f32_16x16x32_bf16 v[36:39], v[148:151], v[186:189], v[36:39]
	v_mfma_f32_16x16x32_bf16 v[32:35], v[166:169], v[186:189], v[32:35]
	v_mfma_f32_16x16x32_bf16 v[20:23], v[148:151], v[194:197], v[20:23]
	v_mfma_f32_16x16x32_bf16 v[16:19], v[166:169], v[194:197], v[16:19]
	v_mfma_f32_16x16x32_bf16 v[4:7], v[148:151], v[210:213], v[4:7]
	v_mfma_f32_16x16x32_bf16 v[0:3], v[166:169], v[210:213], v[0:3]
	s_barrier
	s_add_i32 s40, s40, 2
	s_add_u32 s76, s76, 0x100
	s_addc_u32 s77, s77, 0
	s_add_u32 s38, s38, 0x100
	s_addc_u32 s39, s39, 0
	s_cmp_gt_u32 s40, 5
	s_cbranch_scc0 .LBB0_1132
	s_and_b64 vcc, exec, s[18:19]
	s_cbranch_vccz .LBB0_1135
	s_barrier

.LBB0_1210:
	s_add_u32 s52, s76, 0xfffc0080
	s_addc_u32 s53, s77, -1
	s_add_i32 s87, 0, 0x10000
	s_cmp_eq_u32 s86, 12
	s_cselect_b32 s75, s16, s53
	s_cselect_b32 s74, s17, s52
	s_cselect_b32 s53, s42, s79
	s_cselect_b32 s52, s43, s73
	s_add_i32 s96, 0, 0x14000
	v_add_u32_e32 v132, s87, v242
	v_add_u32_e32 v156, s96, v242
	ds_read_b128 v[120:123], v132
	ds_read_b128 v[124:127], v132 offset:1024
	ds_read_b128 v[128:131], v132 offset:2048
	ds_read_b128 v[132:135], v132 offset:3072
	ds_read_b128 v[144:147], v156
	ds_read_b128 v[148:151], v156 offset:1024
	ds_read_b128 v[152:155], v156 offset:2048
	ds_read_b128 v[156:159], v156 offset:3072
	v_lshl_add_u64 v[198:199], s[76:77], 0, v[166:167]
	s_add_i32 m0, s37, 0xc000
	ds_read_b128 v[170:173], v246
	ds_read_b128 v[174:177], v246 offset:1024
	ds_read_b128 v[178:181], v246 offset:2048
	ds_read_b128 v[182:185], v246 offset:3072
	ds_read_b128 v[186:189], v246 offset:4096
	ds_read_b128 v[190:193], v246 offset:5120
	ds_read_b128 v[194:197], v246 offset:6144
	ds_read_b128 v[206:209], v246 offset:7168
	global_load_lds_dwordx4 v[198:199], off
	v_lshl_add_u64 v[198:199], s[76:77], 0, v[168:169]
	s_add_i32 m0, s37, 0xe000
	s_nop 0
	global_load_lds_dwordx4 v[198:199], off
	s_waitcnt vmcnt(8)
	s_waitcnt lgkmcnt(0)
	s_barrier
	s_waitcnt lgkmcnt(0)
	v_mfma_f32_16x16x32_bf16 v[140:143], v[120:123], v[170:173], v[140:143]
	v_mfma_f32_16x16x32_bf16 v[136:139], v[128:131], v[170:173], v[136:139]
	v_mfma_f32_16x16x32_bf16 v[92:95], v[120:123], v[178:181], v[92:95]
	v_mfma_f32_16x16x32_bf16 v[88:91], v[128:131], v[178:181], v[88:91]
	v_mfma_f32_16x16x32_bf16 v[108:111], v[120:123], v[186:189], v[108:111]
	v_mfma_f32_16x16x32_bf16 v[100:103], v[128:131], v[186:189], v[100:103]
	v_mfma_f32_16x16x32_bf16 v[116:119], v[120:123], v[194:197], v[116:119]
	v_mfma_f32_16x16x32_bf16 v[112:115], v[128:131], v[194:197], v[112:115]
	v_mfma_f32_16x16x32_bf16 v[140:143], v[124:127], v[174:177], v[140:143]
	v_mfma_f32_16x16x32_bf16 v[136:139], v[132:135], v[174:177], v[136:139]
	v_mfma_f32_16x16x32_bf16 v[92:95], v[124:127], v[182:185], v[92:95]
	v_mfma_f32_16x16x32_bf16 v[88:91], v[132:135], v[182:185], v[88:91]
	v_mfma_f32_16x16x32_bf16 v[108:111], v[124:127], v[190:193], v[108:111]
	v_mfma_f32_16x16x32_bf16 v[100:103], v[132:135], v[190:193], v[100:103]
	v_mfma_f32_16x16x32_bf16 v[116:119], v[124:127], v[206:209], v[116:119]
	v_mfma_f32_16x16x32_bf16 v[112:115], v[132:135], v[206:209], v[112:115]
	v_mfma_f32_16x16x32_bf16 v[60:63], v[144:147], v[170:173], v[60:63]
	v_mfma_f32_16x16x32_bf16 v[56:59], v[152:155], v[170:173], v[56:59]
	v_mfma_f32_16x16x32_bf16 v[52:55], v[144:147], v[178:181], v[52:55]
	v_mfma_f32_16x16x32_bf16 v[48:51], v[152:155], v[178:181], v[48:51]
	v_mfma_f32_16x16x32_bf16 v[44:47], v[144:147], v[186:189], v[44:47]
	v_mfma_f32_16x16x32_bf16 v[40:43], v[152:155], v[186:189], v[40:43]
	v_mfma_f32_16x16x32_bf16 v[36:39], v[144:147], v[194:197], v[36:39]
	v_mfma_f32_16x16x32_bf16 v[32:35], v[152:155], v[194:197], v[32:35]
	v_mfma_f32_16x16x32_bf16 v[60:63], v[148:151], v[174:177], v[60:63]
	v_mfma_f32_16x16x32_bf16 v[56:59], v[156:159], v[174:177], v[56:59]
	v_mfma_f32_16x16x32_bf16 v[52:55], v[148:151], v[182:185], v[52:55]
	v_mfma_f32_16x16x32_bf16 v[48:51], v[156:159], v[182:185], v[48:51]
	v_mfma_f32_16x16x32_bf16 v[44:47], v[148:151], v[190:193], v[44:47]
	v_mfma_f32_16x16x32_bf16 v[40:43], v[156:159], v[190:193], v[40:43]
	v_mfma_f32_16x16x32_bf16 v[36:39], v[148:151], v[206:209], v[36:39]
	v_mfma_f32_16x16x32_bf16 v[32:35], v[156:159], v[206:209], v[32:35]
	s_barrier
	s_add_i32 s87, s87, s30
	v_lshl_add_u64 v[198:199], s[52:53], 0, v[200:201]
	s_mov_b32 m0, s87
	ds_read_b128 v[170:173], v246 offset:16384
	ds_read_b128 v[174:177], v246 offset:17408
	ds_read_b128 v[178:181], v246 offset:18432
	ds_read_b128 v[182:185], v246 offset:19456
	ds_read_b128 v[186:189], v246 offset:20480
	ds_read_b128 v[190:193], v246 offset:21504
	ds_read_b128 v[194:197], v246 offset:22528
	ds_read_b128 v[206:209], v246 offset:23552
	global_load_lds_dwordx4 v[198:199], off
	s_add_i32 m0, s87, 0x2000
	s_add_u32 vcc_lo, s52, 0x40000
	v_lshl_add_u64 v[202:203], s[52:53], 0, v[160:161]
	s_addc_u32 vcc_hi, s53, 0
	s_add_i32 s87, s96, s30
	global_load_lds_dwordx4 v[202:203], off
	v_lshl_add_u64 v[204:205], vcc, 0, v[200:201]
	s_mov_b32 m0, s87
	v_lshl_add_u64 v[210:211], s[74:75], 0, v[162:163]
	global_load_lds_dwordx4 v[204:205], off
	v_lshl_add_u64 v[204:205], vcc, 0, v[160:161]
	s_add_i32 m0, s87, 0x2000
	s_nop 0
	global_load_lds_dwordx4 v[204:205], off
	v_lshl_add_u64 v[204:205], s[74:75], 0, v[164:165]
	s_mov_b32 m0, s37
	s_nop 0
	global_load_lds_dwordx4 v[204:205], off
	s_mov_b32 m0, s38
	s_nop 0
	global_load_lds_dwordx4 v[210:211], off
	s_waitcnt vmcnt(8)
	s_waitcnt lgkmcnt(0)
	s_barrier
	s_waitcnt lgkmcnt(0)
	v_mfma_f32_16x16x32_bf16 v[104:107], v[120:123], v[170:173], v[104:107]
	v_mfma_f32_16x16x32_bf16 v[96:99], v[128:131], v[170:173], v[96:99]
	v_mfma_f32_16x16x32_bf16 v[84:87], v[120:123], v[178:181], v[84:87]
	v_mfma_f32_16x16x32_bf16 v[80:83], v[128:131], v[178:181], v[80:83]
	v_mfma_f32_16x16x32_bf16 v[76:79], v[120:123], v[186:189], v[76:79]
	v_mfma_f32_16x16x32_bf16 v[72:75], v[128:131], v[186:189], v[72:75]
	v_mfma_f32_16x16x32_bf16 v[68:71], v[120:123], v[194:197], v[68:71]
	v_mfma_f32_16x16x32_bf16 v[64:67], v[128:131], v[194:197], v[64:67]
	v_mfma_f32_16x16x32_bf16 v[104:107], v[124:127], v[174:177], v[104:107]
	v_mfma_f32_16x16x32_bf16 v[96:99], v[132:135], v[174:177], v[96:99]
	v_mfma_f32_16x16x32_bf16 v[84:87], v[124:127], v[182:185], v[84:87]
	v_mfma_f32_16x16x32_bf16 v[80:83], v[132:135], v[182:185], v[80:83]
	v_mfma_f32_16x16x32_bf16 v[76:79], v[124:127], v[190:193], v[76:79]
	v_mfma_f32_16x16x32_bf16 v[72:75], v[132:135], v[190:193], v[72:75]
	v_mfma_f32_16x16x32_bf16 v[68:71], v[124:127], v[206:209], v[68:71]
	v_mfma_f32_16x16x32_bf16 v[64:67], v[132:135], v[206:209], v[64:67]
	v_mfma_f32_16x16x32_bf16 v[28:31], v[144:147], v[170:173], v[28:31]
	v_mfma_f32_16x16x32_bf16 v[24:27], v[152:155], v[170:173], v[24:27]
	v_mfma_f32_16x16x32_bf16 v[20:23], v[144:147], v[178:181], v[20:23]
	v_mfma_f32_16x16x32_bf16 v[16:19], v[152:155], v[178:181], v[16:19]
	v_mfma_f32_16x16x32_bf16 v[12:15], v[144:147], v[186:189], v[12:15]
	v_mfma_f32_16x16x32_bf16 v[8:11], v[152:155], v[186:189], v[8:11]
	v_mfma_f32_16x16x32_bf16 v[4:7], v[144:147], v[194:197], v[4:7]
	v_mfma_f32_16x16x32_bf16 v[0:3], v[152:155], v[194:197], v[0:3]
	v_mfma_f32_16x16x32_bf16 v[28:31], v[148:151], v[174:177], v[28:31]
	v_mfma_f32_16x16x32_bf16 v[24:27], v[156:159], v[174:177], v[24:27]
	v_mfma_f32_16x16x32_bf16 v[20:23], v[148:151], v[182:185], v[20:23]
	v_mfma_f32_16x16x32_bf16 v[16:19], v[156:159], v[182:185], v[16:19]
	v_mfma_f32_16x16x32_bf16 v[12:15], v[148:151], v[190:193], v[12:15]
	v_mfma_f32_16x16x32_bf16 v[8:11], v[156:159], v[190:193], v[8:11]
	v_mfma_f32_16x16x32_bf16 v[4:7], v[148:151], v[206:209], v[4:7]
	v_mfma_f32_16x16x32_bf16 v[0:3], v[156:159], v[206:209], v[0:3]
	s_barrier
	s_add_i32 s87, 0, 0x18000
	s_add_i32 s96, 0, 0x1c000
	v_add_u32_e32 v132, s87, v242
	v_add_u32_e32 v156, s96, v242
	ds_read_b128 v[120:123], v132
	ds_read_b128 v[124:127], v132 offset:1024
	ds_read_b128 v[128:131], v132 offset:2048
	ds_read_b128 v[132:135], v132 offset:3072
	ds_read_b128 v[144:147], v156
	ds_read_b128 v[148:151], v156 offset:1024
	ds_read_b128 v[152:155], v156 offset:2048
	ds_read_b128 v[156:159], v156 offset:3072
	s_add_u32 s74, s74, 0x40000
	s_addc_u32 s75, s75, 0
	s_mov_b32 m0, s39
	v_lshl_add_u64 v[212:213], s[74:75], 0, v[164:165]
	ds_read_b128 v[170:173], v246 offset:32768
	ds_read_b128 v[174:177], v246 offset:33792
	ds_read_b128 v[178:181], v246 offset:34816
	ds_read_b128 v[182:185], v246 offset:35840
	ds_read_b128 v[186:189], v246 offset:36864
	ds_read_b128 v[190:193], v246 offset:37888
	ds_read_b128 v[194:197], v246 offset:38912
	ds_read_b128 v[206:209], v246 offset:39936
	global_load_lds_dwordx4 v[212:213], off
	v_lshl_add_u64 v[212:213], s[74:75], 0, v[162:163]
	s_mov_b32 m0, s50
	s_nop 0
	global_load_lds_dwordx4 v[212:213], off
	s_waitcnt vmcnt(8)
	s_waitcnt lgkmcnt(0)
	s_barrier
	s_waitcnt lgkmcnt(0)
	v_mfma_f32_16x16x32_bf16 v[140:143], v[120:123], v[170:173], v[140:143]
	v_mfma_f32_16x16x32_bf16 v[136:139], v[128:131], v[170:173], v[136:139]
	v_mfma_f32_16x16x32_bf16 v[92:95], v[120:123], v[178:181], v[92:95]
	v_mfma_f32_16x16x32_bf16 v[88:91], v[128:131], v[178:181], v[88:91]
	v_mfma_f32_16x16x32_bf16 v[108:111], v[120:123], v[186:189], v[108:111]
	v_mfma_f32_16x16x32_bf16 v[100:103], v[128:131], v[186:189], v[100:103]
	v_mfma_f32_16x16x32_bf16 v[116:119], v[120:123], v[194:197], v[116:119]
	v_mfma_f32_16x16x32_bf16 v[112:115], v[128:131], v[194:197], v[112:115]
	v_mfma_f32_16x16x32_bf16 v[140:143], v[124:127], v[174:177], v[140:143]
	v_mfma_f32_16x16x32_bf16 v[136:139], v[132:135], v[174:177], v[136:139]
	v_mfma_f32_16x16x32_bf16 v[92:95], v[124:127], v[182:185], v[92:95]
	v_mfma_f32_16x16x32_bf16 v[88:91], v[132:135], v[182:185], v[88:91]
	v_mfma_f32_16x16x32_bf16 v[108:111], v[124:127], v[190:193], v[108:111]
	v_mfma_f32_16x16x32_bf16 v[100:103], v[132:135], v[190:193], v[100:103]
	v_mfma_f32_16x16x32_bf16 v[116:119], v[124:127], v[206:209], v[116:119]
	v_mfma_f32_16x16x32_bf16 v[112:115], v[132:135], v[206:209], v[112:115]
	v_mfma_f32_16x16x32_bf16 v[60:63], v[144:147], v[170:173], v[60:63]
	v_mfma_f32_16x16x32_bf16 v[56:59], v[152:155], v[170:173], v[56:59]
	v_mfma_f32_16x16x32_bf16 v[52:55], v[144:147], v[178:181], v[52:55]
	v_mfma_f32_16x16x32_bf16 v[48:51], v[152:155], v[178:181], v[48:51]
	v_mfma_f32_16x16x32_bf16 v[44:47], v[144:147], v[186:189], v[44:47]
	v_mfma_f32_16x16x32_bf16 v[40:43], v[152:155], v[186:189], v[40:43]
	v_mfma_f32_16x16x32_bf16 v[36:39], v[144:147], v[194:197], v[36:39]
	v_mfma_f32_16x16x32_bf16 v[32:35], v[152:155], v[194:197], v[32:35]
	v_mfma_f32_16x16x32_bf16 v[60:63], v[148:151], v[174:177], v[60:63]
	v_mfma_f32_16x16x32_bf16 v[56:59], v[156:159], v[174:177], v[56:59]
	v_mfma_f32_16x16x32_bf16 v[52:55], v[148:151], v[182:185], v[52:55]
	v_mfma_f32_16x16x32_bf16 v[48:51], v[156:159], v[182:185], v[48:51]
	v_mfma_f32_16x16x32_bf16 v[44:47], v[148:151], v[190:193], v[44:47]
	v_mfma_f32_16x16x32_bf16 v[40:43], v[156:159], v[190:193], v[40:43]
	v_mfma_f32_16x16x32_bf16 v[36:39], v[148:151], v[206:209], v[36:39]
	v_mfma_f32_16x16x32_bf16 v[32:35], v[156:159], v[206:209], v[32:35]
	s_barrier
	s_add_i32 s74, s87, s30
	v_lshl_add_u64 v[198:199], v[198:199], 0, s[20:21]
	s_mov_b32 m0, s74
	ds_read_b128 v[170:173], v246 offset:49152
	ds_read_b128 v[174:177], v246 offset:50176
	ds_read_b128 v[178:181], v246 offset:51200
	ds_read_b128 v[182:185], v246 offset:52224
	ds_read_b128 v[186:189], v246 offset:53248
	ds_read_b128 v[190:193], v246 offset:54272
	ds_read_b128 v[194:197], v246 offset:55296
	ds_read_b128 v[206:209], v246 offset:56320
	global_load_lds_dwordx4 v[198:199], off
	s_add_i32 m0, s74, 0x2000
	s_add_u32 s52, s52, 0x40080
	v_lshl_add_u64 v[198:199], v[202:203], 0, s[20:21]
	s_addc_u32 s53, s53, 0
	s_add_i32 s74, s96, s30
	global_load_lds_dwordx4 v[198:199], off
	v_lshl_add_u64 v[198:199], s[52:53], 0, v[200:201]
	s_mov_b32 m0, s74
	s_nop 0
	global_load_lds_dwordx4 v[198:199], off
	v_lshl_add_u64 v[198:199], s[52:53], 0, v[160:161]
	s_add_i32 m0, s74, 0x2000
	s_nop 0
	global_load_lds_dwordx4 v[198:199], off
	v_lshl_add_u64 v[198:199], v[204:205], 0, s[20:21]
	s_mov_b32 m0, s89
	s_nop 0
	global_load_lds_dwordx4 v[198:199], off
	v_lshl_add_u64 v[198:199], v[210:211], 0, s[20:21]
	s_mov_b32 m0, s92
	s_nop 0
	global_load_lds_dwordx4 v[198:199], off
	s_waitcnt vmcnt(8)
	s_waitcnt lgkmcnt(0)
	s_barrier
	s_waitcnt lgkmcnt(0)
	v_mfma_f32_16x16x32_bf16 v[104:107], v[120:123], v[170:173], v[104:107]
	v_mfma_f32_16x16x32_bf16 v[96:99], v[128:131], v[170:173], v[96:99]
	v_mfma_f32_16x16x32_bf16 v[84:87], v[120:123], v[178:181], v[84:87]
	v_mfma_f32_16x16x32_bf16 v[80:83], v[128:131], v[178:181], v[80:83]
	v_mfma_f32_16x16x32_bf16 v[76:79], v[120:123], v[186:189], v[76:79]
	v_mfma_f32_16x16x32_bf16 v[72:75], v[128:131], v[186:189], v[72:75]
	v_mfma_f32_16x16x32_bf16 v[68:71], v[120:123], v[194:197], v[68:71]
	v_mfma_f32_16x16x32_bf16 v[64:67], v[128:131], v[194:197], v[64:67]
	v_mfma_f32_16x16x32_bf16 v[104:107], v[124:127], v[174:177], v[104:107]
	v_mfma_f32_16x16x32_bf16 v[96:99], v[132:135], v[174:177], v[96:99]
	v_mfma_f32_16x16x32_bf16 v[84:87], v[124:127], v[182:185], v[84:87]
	v_mfma_f32_16x16x32_bf16 v[80:83], v[132:135], v[182:185], v[80:83]
	v_mfma_f32_16x16x32_bf16 v[76:79], v[124:127], v[190:193], v[76:79]
	v_mfma_f32_16x16x32_bf16 v[72:75], v[132:135], v[190:193], v[72:75]
	v_mfma_f32_16x16x32_bf16 v[68:71], v[124:127], v[206:209], v[68:71]
	v_mfma_f32_16x16x32_bf16 v[64:67], v[132:135], v[206:209], v[64:67]
	v_mfma_f32_16x16x32_bf16 v[28:31], v[144:147], v[170:173], v[28:31]
	v_mfma_f32_16x16x32_bf16 v[24:27], v[152:155], v[170:173], v[24:27]
	v_mfma_f32_16x16x32_bf16 v[20:23], v[144:147], v[178:181], v[20:23]
	v_mfma_f32_16x16x32_bf16 v[16:19], v[152:155], v[178:181], v[16:19]
	v_mfma_f32_16x16x32_bf16 v[12:15], v[144:147], v[186:189], v[12:15]
	v_mfma_f32_16x16x32_bf16 v[8:11], v[152:155], v[186:189], v[8:11]
	v_mfma_f32_16x16x32_bf16 v[4:7], v[144:147], v[194:197], v[4:7]
	v_mfma_f32_16x16x32_bf16 v[0:3], v[152:155], v[194:197], v[0:3]
	v_mfma_f32_16x16x32_bf16 v[28:31], v[148:151], v[174:177], v[28:31]
	v_mfma_f32_16x16x32_bf16 v[24:27], v[156:159], v[174:177], v[24:27]
	v_mfma_f32_16x16x32_bf16 v[20:23], v[148:151], v[182:185], v[20:23]
	v_mfma_f32_16x16x32_bf16 v[16:19], v[156:159], v[182:185], v[16:19]
	v_mfma_f32_16x16x32_bf16 v[12:15], v[148:151], v[190:193], v[12:15]
	v_mfma_f32_16x16x32_bf16 v[8:11], v[156:159], v[190:193], v[8:11]
	v_mfma_f32_16x16x32_bf16 v[4:7], v[148:151], v[206:209], v[4:7]
	v_mfma_f32_16x16x32_bf16 v[0:3], v[156:159], v[206:209], v[0:3]
	s_barrier
	s_add_i32 s86, s86, 2
	s_add_u32 s76, s76, 0x100
	s_addc_u32 s77, s77, 0
	s_add_u32 s73, s73, 0x100
	s_addc_u32 s79, s79, 0
	s_cmp_gt_u32 s86, 13
	s_cbranch_scc0 .LBB0_1210
	v_mov_b64_e32 v[230:231], 0x100
	s_and_b64 vcc, exec, s[24:25]
	s_cbranch_vccz .LBB0_1213
	s_barrier

.LBB0_1304:
	s_add_u32 s52, s8, 0xfffc0080
	s_addc_u32 s53, s9, -1
	s_add_i32 s83, 0, 0x10000
	s_cmp_eq_u32 s82, 12
	s_cselect_b32 s75, s23, s53
	s_cselect_b32 s74, s42, s52
	s_cselect_b32 s53, s19, s81
	s_cselect_b32 s52, s43, s80
	s_add_i32 s86, 0, 0x14000
	v_add_u32_e32 v92, s83, v163
	v_add_u32_e32 v170, s86, v163
	ds_read_b128 v[80:83], v92
	ds_read_b128 v[84:87], v92 offset:1024
	ds_read_b128 v[88:91], v92 offset:2048
	ds_read_b128 v[92:95], v92 offset:3072
	ds_read_b128 v[154:157], v170
	ds_read_b128 v[158:161], v170 offset:1024
	ds_read_b128 v[166:169], v170 offset:2048
	ds_read_b128 v[170:173], v170 offset:3072
	v_lshl_add_u64 v[198:199], s[8:9], 0, v[150:151]
	s_add_i32 m0, s37, 0xc000
	ds_read_b128 v[174:177], v165
	ds_read_b128 v[178:181], v165 offset:1024
	ds_read_b128 v[182:185], v165 offset:2048
	ds_read_b128 v[186:189], v165 offset:3072
	ds_read_b128 v[190:193], v165 offset:4096
	ds_read_b128 v[194:197], v165 offset:5120
	ds_read_b128 v[202:205], v165 offset:6144
	ds_read_b128 v[206:209], v165 offset:7168
	global_load_lds_dwordx4 v[198:199], off
	v_lshl_add_u64 v[198:199], s[8:9], 0, v[152:153]
	s_add_i32 m0, s37, 0xe000
	s_nop 0
	global_load_lds_dwordx4 v[198:199], off
	s_waitcnt vmcnt(8)
	s_waitcnt lgkmcnt(0)
	s_barrier
	s_waitcnt lgkmcnt(0)
	v_mfma_f32_16x16x32_bf16 v[140:143], v[80:83], v[174:177], v[140:143]
	v_mfma_f32_16x16x32_bf16 v[136:139], v[88:91], v[174:177], v[136:139]
	v_mfma_f32_16x16x32_bf16 v[124:127], v[80:83], v[182:185], v[124:127]
	v_mfma_f32_16x16x32_bf16 v[120:123], v[88:91], v[182:185], v[120:123]
	v_mfma_f32_16x16x32_bf16 v[108:111], v[80:83], v[190:193], v[108:111]
	v_mfma_f32_16x16x32_bf16 v[104:107], v[88:91], v[190:193], v[104:107]
	v_mfma_f32_16x16x32_bf16 v[76:79], v[80:83], v[202:205], v[76:79]
	v_mfma_f32_16x16x32_bf16 v[72:75], v[88:91], v[202:205], v[72:75]
	v_mfma_f32_16x16x32_bf16 v[140:143], v[84:87], v[178:181], v[140:143]
	v_mfma_f32_16x16x32_bf16 v[136:139], v[92:95], v[178:181], v[136:139]
	v_mfma_f32_16x16x32_bf16 v[124:127], v[84:87], v[186:189], v[124:127]
	v_mfma_f32_16x16x32_bf16 v[120:123], v[92:95], v[186:189], v[120:123]
	v_mfma_f32_16x16x32_bf16 v[108:111], v[84:87], v[194:197], v[108:111]
	v_mfma_f32_16x16x32_bf16 v[104:107], v[92:95], v[194:197], v[104:107]
	v_mfma_f32_16x16x32_bf16 v[76:79], v[84:87], v[206:209], v[76:79]
	v_mfma_f32_16x16x32_bf16 v[72:75], v[92:95], v[206:209], v[72:75]
	v_mfma_f32_16x16x32_bf16 v[132:135], v[154:157], v[174:177], v[132:135]
	v_mfma_f32_16x16x32_bf16 v[128:131], v[166:169], v[174:177], v[128:131]
	v_mfma_f32_16x16x32_bf16 v[116:119], v[154:157], v[182:185], v[116:119]
	v_mfma_f32_16x16x32_bf16 v[112:115], v[166:169], v[182:185], v[112:115]
	v_mfma_f32_16x16x32_bf16 v[100:103], v[154:157], v[190:193], v[100:103]
	v_mfma_f32_16x16x32_bf16 v[96:99], v[166:169], v[190:193], v[96:99]
	v_mfma_f32_16x16x32_bf16 v[68:71], v[154:157], v[202:205], v[68:71]
	v_mfma_f32_16x16x32_bf16 v[64:67], v[166:169], v[202:205], v[64:67]
	v_mfma_f32_16x16x32_bf16 v[132:135], v[158:161], v[178:181], v[132:135]
	v_mfma_f32_16x16x32_bf16 v[128:131], v[170:173], v[178:181], v[128:131]
	v_mfma_f32_16x16x32_bf16 v[116:119], v[158:161], v[186:189], v[116:119]
	v_mfma_f32_16x16x32_bf16 v[112:115], v[170:173], v[186:189], v[112:115]
	v_mfma_f32_16x16x32_bf16 v[100:103], v[158:161], v[194:197], v[100:103]
	v_mfma_f32_16x16x32_bf16 v[96:99], v[170:173], v[194:197], v[96:99]
	v_mfma_f32_16x16x32_bf16 v[68:71], v[158:161], v[206:209], v[68:71]
	v_mfma_f32_16x16x32_bf16 v[64:67], v[170:173], v[206:209], v[64:67]
	s_barrier
	s_add_i32 s83, s83, s36
	v_lshl_add_u64 v[198:199], s[52:53], 0, v[200:201]
	s_mov_b32 m0, s83
	ds_read_b128 v[174:177], v165 offset:16384
	ds_read_b128 v[178:181], v165 offset:17408
	ds_read_b128 v[182:185], v165 offset:18432
	ds_read_b128 v[186:189], v165 offset:19456
	ds_read_b128 v[190:193], v165 offset:20480
	ds_read_b128 v[194:197], v165 offset:21504
	ds_read_b128 v[202:205], v165 offset:22528
	ds_read_b128 v[206:209], v165 offset:23552
	global_load_lds_dwordx4 v[198:199], off
	s_add_i32 m0, s83, 0x2000
	s_add_u32 s84, s52, 0x40000
	v_lshl_add_u64 v[210:211], s[52:53], 0, v[144:145]
	s_addc_u32 s85, s53, 0
	s_add_i32 s83, s86, s36
	global_load_lds_dwordx4 v[210:211], off
	v_lshl_add_u64 v[212:213], s[84:85], 0, v[200:201]
	s_mov_b32 m0, s83
	v_lshl_add_u64 v[214:215], s[74:75], 0, v[146:147]
	global_load_lds_dwordx4 v[212:213], off
	v_lshl_add_u64 v[212:213], s[84:85], 0, v[144:145]
	s_add_i32 m0, s83, 0x2000
	s_nop 0
	global_load_lds_dwordx4 v[212:213], off
	v_lshl_add_u64 v[212:213], s[74:75], 0, v[148:149]
	s_mov_b32 m0, s37
	s_nop 0
	global_load_lds_dwordx4 v[212:213], off
	s_mov_b32 m0, s38
	s_nop 0
	global_load_lds_dwordx4 v[214:215], off
	s_waitcnt vmcnt(8)
	s_waitcnt lgkmcnt(0)
	s_barrier
	s_waitcnt lgkmcnt(0)
	v_mfma_f32_16x16x32_bf16 v[60:63], v[80:83], v[174:177], v[60:63]
	v_mfma_f32_16x16x32_bf16 v[56:59], v[88:91], v[174:177], v[56:59]
	v_mfma_f32_16x16x32_bf16 v[44:47], v[80:83], v[182:185], v[44:47]
	v_mfma_f32_16x16x32_bf16 v[40:43], v[88:91], v[182:185], v[40:43]
	v_mfma_f32_16x16x32_bf16 v[28:31], v[80:83], v[190:193], v[28:31]
	v_mfma_f32_16x16x32_bf16 v[24:27], v[88:91], v[190:193], v[24:27]
	v_mfma_f32_16x16x32_bf16 v[12:15], v[80:83], v[202:205], v[12:15]
	v_mfma_f32_16x16x32_bf16 v[8:11], v[88:91], v[202:205], v[8:11]
	v_mfma_f32_16x16x32_bf16 v[60:63], v[84:87], v[178:181], v[60:63]
	v_mfma_f32_16x16x32_bf16 v[56:59], v[92:95], v[178:181], v[56:59]
	v_mfma_f32_16x16x32_bf16 v[44:47], v[84:87], v[186:189], v[44:47]
	v_mfma_f32_16x16x32_bf16 v[40:43], v[92:95], v[186:189], v[40:43]
	v_mfma_f32_16x16x32_bf16 v[28:31], v[84:87], v[194:197], v[28:31]
	v_mfma_f32_16x16x32_bf16 v[24:27], v[92:95], v[194:197], v[24:27]
	v_mfma_f32_16x16x32_bf16 v[12:15], v[84:87], v[206:209], v[12:15]
	v_mfma_f32_16x16x32_bf16 v[8:11], v[92:95], v[206:209], v[8:11]
	v_mfma_f32_16x16x32_bf16 v[52:55], v[154:157], v[174:177], v[52:55]
	v_mfma_f32_16x16x32_bf16 v[48:51], v[166:169], v[174:177], v[48:51]
	v_mfma_f32_16x16x32_bf16 v[36:39], v[154:157], v[182:185], v[36:39]
	v_mfma_f32_16x16x32_bf16 v[32:35], v[166:169], v[182:185], v[32:35]
	v_mfma_f32_16x16x32_bf16 v[20:23], v[154:157], v[190:193], v[20:23]
	v_mfma_f32_16x16x32_bf16 v[16:19], v[166:169], v[190:193], v[16:19]
	v_mfma_f32_16x16x32_bf16 v[4:7], v[154:157], v[202:205], v[4:7]
	v_mfma_f32_16x16x32_bf16 v[0:3], v[166:169], v[202:205], v[0:3]
	v_mfma_f32_16x16x32_bf16 v[52:55], v[158:161], v[178:181], v[52:55]
	v_mfma_f32_16x16x32_bf16 v[48:51], v[170:173], v[178:181], v[48:51]
	v_mfma_f32_16x16x32_bf16 v[36:39], v[158:161], v[186:189], v[36:39]
	v_mfma_f32_16x16x32_bf16 v[32:35], v[170:173], v[186:189], v[32:35]
	v_mfma_f32_16x16x32_bf16 v[20:23], v[158:161], v[194:197], v[20:23]
	v_mfma_f32_16x16x32_bf16 v[16:19], v[170:173], v[194:197], v[16:19]
	v_mfma_f32_16x16x32_bf16 v[4:7], v[158:161], v[206:209], v[4:7]
	v_mfma_f32_16x16x32_bf16 v[0:3], v[170:173], v[206:209], v[0:3]
	s_barrier
	s_add_i32 s83, 0, 0x18000
	s_add_i32 s84, 0, 0x1c000
	v_add_u32_e32 v92, s83, v163
	v_add_u32_e32 v170, s84, v163
	ds_read_b128 v[80:83], v92
	ds_read_b128 v[84:87], v92 offset:1024
	ds_read_b128 v[88:91], v92 offset:2048
	ds_read_b128 v[92:95], v92 offset:3072
	ds_read_b128 v[154:157], v170
	ds_read_b128 v[158:161], v170 offset:1024
	ds_read_b128 v[166:169], v170 offset:2048
	ds_read_b128 v[170:173], v170 offset:3072
	s_add_u32 s74, s74, 0x40000
	s_addc_u32 s75, s75, 0
	s_mov_b32 m0, s39
	v_lshl_add_u64 v[216:217], s[74:75], 0, v[148:149]
	ds_read_b128 v[174:177], v165 offset:32768
	ds_read_b128 v[178:181], v165 offset:33792
	ds_read_b128 v[182:185], v165 offset:34816
	ds_read_b128 v[186:189], v165 offset:35840
	ds_read_b128 v[190:193], v165 offset:36864
	ds_read_b128 v[194:197], v165 offset:37888
	ds_read_b128 v[202:205], v165 offset:38912
	ds_read_b128 v[206:209], v165 offset:39936
	global_load_lds_dwordx4 v[216:217], off
	v_lshl_add_u64 v[216:217], s[74:75], 0, v[146:147]
	s_mov_b32 m0, s50
	s_nop 0
	global_load_lds_dwordx4 v[216:217], off
	s_waitcnt vmcnt(8)
	s_waitcnt lgkmcnt(0)
	s_barrier
	s_waitcnt lgkmcnt(0)
	v_mfma_f32_16x16x32_bf16 v[140:143], v[80:83], v[174:177], v[140:143]
	v_mfma_f32_16x16x32_bf16 v[136:139], v[88:91], v[174:177], v[136:139]
	v_mfma_f32_16x16x32_bf16 v[124:127], v[80:83], v[182:185], v[124:127]
	v_mfma_f32_16x16x32_bf16 v[120:123], v[88:91], v[182:185], v[120:123]
	v_mfma_f32_16x16x32_bf16 v[108:111], v[80:83], v[190:193], v[108:111]
	v_mfma_f32_16x16x32_bf16 v[104:107], v[88:91], v[190:193], v[104:107]
	v_mfma_f32_16x16x32_bf16 v[76:79], v[80:83], v[202:205], v[76:79]
	v_mfma_f32_16x16x32_bf16 v[72:75], v[88:91], v[202:205], v[72:75]
	v_mfma_f32_16x16x32_bf16 v[140:143], v[84:87], v[178:181], v[140:143]
	v_mfma_f32_16x16x32_bf16 v[136:139], v[92:95], v[178:181], v[136:139]
	v_mfma_f32_16x16x32_bf16 v[124:127], v[84:87], v[186:189], v[124:127]
	v_mfma_f32_16x16x32_bf16 v[120:123], v[92:95], v[186:189], v[120:123]
	v_mfma_f32_16x16x32_bf16 v[108:111], v[84:87], v[194:197], v[108:111]
	v_mfma_f32_16x16x32_bf16 v[104:107], v[92:95], v[194:197], v[104:107]
	v_mfma_f32_16x16x32_bf16 v[76:79], v[84:87], v[206:209], v[76:79]
	v_mfma_f32_16x16x32_bf16 v[72:75], v[92:95], v[206:209], v[72:75]
	v_mfma_f32_16x16x32_bf16 v[132:135], v[154:157], v[174:177], v[132:135]
	v_mfma_f32_16x16x32_bf16 v[128:131], v[166:169], v[174:177], v[128:131]
	v_mfma_f32_16x16x32_bf16 v[116:119], v[154:157], v[182:185], v[116:119]
	v_mfma_f32_16x16x32_bf16 v[112:115], v[166:169], v[182:185], v[112:115]
	v_mfma_f32_16x16x32_bf16 v[100:103], v[154:157], v[190:193], v[100:103]
	v_mfma_f32_16x16x32_bf16 v[96:99], v[166:169], v[190:193], v[96:99]
	v_mfma_f32_16x16x32_bf16 v[68:71], v[154:157], v[202:205], v[68:71]
	v_mfma_f32_16x16x32_bf16 v[64:67], v[166:169], v[202:205], v[64:67]
	v_mfma_f32_16x16x32_bf16 v[132:135], v[158:161], v[178:181], v[132:135]
	v_mfma_f32_16x16x32_bf16 v[128:131], v[170:173], v[178:181], v[128:131]
	v_mfma_f32_16x16x32_bf16 v[116:119], v[158:161], v[186:189], v[116:119]
	v_mfma_f32_16x16x32_bf16 v[112:115], v[170:173], v[186:189], v[112:115]
	v_mfma_f32_16x16x32_bf16 v[100:103], v[158:161], v[194:197], v[100:103]
	v_mfma_f32_16x16x32_bf16 v[96:99], v[170:173], v[194:197], v[96:99]
	v_mfma_f32_16x16x32_bf16 v[68:71], v[158:161], v[206:209], v[68:71]
	v_mfma_f32_16x16x32_bf16 v[64:67], v[170:173], v[206:209], v[64:67]
	s_barrier
	s_add_i32 s74, s83, s36
	v_lshl_add_u64 v[198:199], v[198:199], 0, s[20:21]
	s_mov_b32 m0, s74
	ds_read_b128 v[174:177], v165 offset:49152
	ds_read_b128 v[178:181], v165 offset:50176
	ds_read_b128 v[182:185], v165 offset:51200
	ds_read_b128 v[186:189], v165 offset:52224
	ds_read_b128 v[190:193], v165 offset:53248
	ds_read_b128 v[194:197], v165 offset:54272
	ds_read_b128 v[202:205], v165 offset:55296
	ds_read_b128 v[206:209], v165 offset:56320
	global_load_lds_dwordx4 v[198:199], off
	s_add_i32 m0, s74, 0x2000
	s_add_u32 s52, s52, 0x40080
	v_lshl_add_u64 v[198:199], v[210:211], 0, s[20:21]
	s_addc_u32 s53, s53, 0
	s_add_i32 s74, s84, s36
	global_load_lds_dwordx4 v[198:199], off
	v_lshl_add_u64 v[198:199], s[52:53], 0, v[200:201]
	s_mov_b32 m0, s74
	s_nop 0
	global_load_lds_dwordx4 v[198:199], off
	v_lshl_add_u64 v[198:199], s[52:53], 0, v[144:145]
	s_add_i32 m0, s74, 0x2000
	s_nop 0
	global_load_lds_dwordx4 v[198:199], off
	v_lshl_add_u64 v[198:199], v[212:213], 0, s[20:21]
	s_mov_b32 m0, s77
	s_nop 0
	global_load_lds_dwordx4 v[198:199], off
	v_lshl_add_u64 v[198:199], v[214:215], 0, s[20:21]
	s_mov_b32 m0, s78
	s_nop 0
	global_load_lds_dwordx4 v[198:199], off
	s_waitcnt vmcnt(8)
	s_waitcnt lgkmcnt(0)
	s_barrier
	s_waitcnt lgkmcnt(0)
	v_mfma_f32_16x16x32_bf16 v[60:63], v[80:83], v[174:177], v[60:63]
	v_mfma_f32_16x16x32_bf16 v[56:59], v[88:91], v[174:177], v[56:59]
	v_mfma_f32_16x16x32_bf16 v[44:47], v[80:83], v[182:185], v[44:47]
	v_mfma_f32_16x16x32_bf16 v[40:43], v[88:91], v[182:185], v[40:43]
	v_mfma_f32_16x16x32_bf16 v[28:31], v[80:83], v[190:193], v[28:31]
	v_mfma_f32_16x16x32_bf16 v[24:27], v[88:91], v[190:193], v[24:27]
	v_mfma_f32_16x16x32_bf16 v[12:15], v[80:83], v[202:205], v[12:15]
	v_mfma_f32_16x16x32_bf16 v[8:11], v[88:91], v[202:205], v[8:11]
	v_mfma_f32_16x16x32_bf16 v[60:63], v[84:87], v[178:181], v[60:63]
	v_mfma_f32_16x16x32_bf16 v[56:59], v[92:95], v[178:181], v[56:59]
	v_mfma_f32_16x16x32_bf16 v[44:47], v[84:87], v[186:189], v[44:47]
	v_mfma_f32_16x16x32_bf16 v[40:43], v[92:95], v[186:189], v[40:43]
	v_mfma_f32_16x16x32_bf16 v[28:31], v[84:87], v[194:197], v[28:31]
	v_mfma_f32_16x16x32_bf16 v[24:27], v[92:95], v[194:197], v[24:27]
	v_mfma_f32_16x16x32_bf16 v[12:15], v[84:87], v[206:209], v[12:15]
	v_mfma_f32_16x16x32_bf16 v[8:11], v[92:95], v[206:209], v[8:11]
	v_mfma_f32_16x16x32_bf16 v[52:55], v[154:157], v[174:177], v[52:55]
	v_mfma_f32_16x16x32_bf16 v[48:51], v[166:169], v[174:177], v[48:51]
	v_mfma_f32_16x16x32_bf16 v[36:39], v[154:157], v[182:185], v[36:39]
	v_mfma_f32_16x16x32_bf16 v[32:35], v[166:169], v[182:185], v[32:35]
	v_mfma_f32_16x16x32_bf16 v[20:23], v[154:157], v[190:193], v[20:23]
	v_mfma_f32_16x16x32_bf16 v[16:19], v[166:169], v[190:193], v[16:19]
	v_mfma_f32_16x16x32_bf16 v[4:7], v[154:157], v[202:205], v[4:7]
	v_mfma_f32_16x16x32_bf16 v[0:3], v[166:169], v[202:205], v[0:3]
	v_mfma_f32_16x16x32_bf16 v[52:55], v[158:161], v[178:181], v[52:55]
	v_mfma_f32_16x16x32_bf16 v[48:51], v[170:173], v[178:181], v[48:51]
	v_mfma_f32_16x16x32_bf16 v[36:39], v[158:161], v[186:189], v[36:39]
	v_mfma_f32_16x16x32_bf16 v[32:35], v[170:173], v[186:189], v[32:35]
	v_mfma_f32_16x16x32_bf16 v[20:23], v[158:161], v[194:197], v[20:23]
	v_mfma_f32_16x16x32_bf16 v[16:19], v[170:173], v[194:197], v[16:19]
	v_mfma_f32_16x16x32_bf16 v[4:7], v[158:161], v[206:209], v[4:7]
	v_mfma_f32_16x16x32_bf16 v[0:3], v[170:173], v[206:209], v[0:3]
	s_barrier
	s_add_i32 s82, s82, 2
	s_add_u32 s8, s8, 0x100
	s_addc_u32 s9, s9, 0
	s_add_u32 s80, s80, 0x100
	s_addc_u32 s81, s81, 0
	s_cmp_gt_u32 s82, 13
	s_cbranch_scc0 .LBB0_1304
	s_and_b64 vcc, exec, s[16:17]
	s_movk_i32 s43, 0xd8
	s_cbranch_vccz .LBB0_1307
	s_barrier

.LBB0_1379:
	s_add_u32 s52, s10, 0xfff00080
	s_addc_u32 s53, s11, -1
	s_add_i32 s95, 0, 0x10000
	s_cmp_eq_u32 s94, 60
	s_cselect_b32 s75, s50, s53
	s_cselect_b32 s74, s51, s52
	s_cselect_b32 s53, s77, s87
	s_cselect_b32 s52, s79, s86
	s_add_i32 s96, 0, 0x14000
	v_add_u32_e32 v140, s95, v225
	v_add_u32_e32 v156, s96, v225
	ds_read_b128 v[128:131], v140
	ds_read_b128 v[132:135], v140 offset:1024
	ds_read_b128 v[136:139], v140 offset:2048
	ds_read_b128 v[140:143], v140 offset:3072
	ds_read_b128 v[144:147], v156
	ds_read_b128 v[148:151], v156 offset:1024
	ds_read_b128 v[152:155], v156 offset:2048
	ds_read_b128 v[156:159], v156 offset:3072
	v_lshl_add_u64 v[198:199], s[10:11], 0, v[174:175]
	s_add_i32 m0, s37, 0xc000
	ds_read_b128 v[160:163], v242
	ds_read_b128 v[164:167], v242 offset:1024
	ds_read_b128 v[178:181], v242 offset:2048
	ds_read_b128 v[182:185], v242 offset:3072
	ds_read_b128 v[186:189], v242 offset:4096
	ds_read_b128 v[190:193], v242 offset:5120
	ds_read_b128 v[194:197], v242 offset:6144
	ds_read_b128 v[202:205], v242 offset:7168
	global_load_lds_dwordx4 v[198:199], off
	v_lshl_add_u64 v[198:199], s[10:11], 0, v[176:177]
	s_add_i32 m0, s37, 0xe000
	s_nop 0
	global_load_lds_dwordx4 v[198:199], off
	s_waitcnt vmcnt(8)
	s_waitcnt lgkmcnt(0)
	s_barrier
	s_waitcnt lgkmcnt(0)
	v_mfma_f32_16x16x32_bf16 v[104:107], v[128:131], v[160:163], v[104:107]
	v_mfma_f32_16x16x32_bf16 v[96:99], v[136:139], v[160:163], v[96:99]
	v_mfma_f32_16x16x32_bf16 v[120:123], v[128:131], v[178:181], v[120:123]
	v_mfma_f32_16x16x32_bf16 v[124:127], v[136:139], v[178:181], v[124:127]
	v_mfma_f32_16x16x32_bf16 v[116:119], v[128:131], v[186:189], v[116:119]
	v_mfma_f32_16x16x32_bf16 v[112:115], v[136:139], v[186:189], v[112:115]
	v_mfma_f32_16x16x32_bf16 v[108:111], v[128:131], v[194:197], v[108:111]
	v_mfma_f32_16x16x32_bf16 v[100:103], v[136:139], v[194:197], v[100:103]
	v_mfma_f32_16x16x32_bf16 v[104:107], v[132:135], v[164:167], v[104:107]
	v_mfma_f32_16x16x32_bf16 v[96:99], v[140:143], v[164:167], v[96:99]
	v_mfma_f32_16x16x32_bf16 v[120:123], v[132:135], v[182:185], v[120:123]
	v_mfma_f32_16x16x32_bf16 v[124:127], v[140:143], v[182:185], v[124:127]
	v_mfma_f32_16x16x32_bf16 v[116:119], v[132:135], v[190:193], v[116:119]
	v_mfma_f32_16x16x32_bf16 v[112:115], v[140:143], v[190:193], v[112:115]
	v_mfma_f32_16x16x32_bf16 v[108:111], v[132:135], v[202:205], v[108:111]
	v_mfma_f32_16x16x32_bf16 v[100:103], v[140:143], v[202:205], v[100:103]
	v_mfma_f32_16x16x32_bf16 v[60:63], v[144:147], v[160:163], v[60:63]
	v_mfma_f32_16x16x32_bf16 v[56:59], v[152:155], v[160:163], v[56:59]
	v_mfma_f32_16x16x32_bf16 v[52:55], v[144:147], v[178:181], v[52:55]
	v_mfma_f32_16x16x32_bf16 v[48:51], v[152:155], v[178:181], v[48:51]
	v_mfma_f32_16x16x32_bf16 v[44:47], v[144:147], v[186:189], v[44:47]
	v_mfma_f32_16x16x32_bf16 v[40:43], v[152:155], v[186:189], v[40:43]
	v_mfma_f32_16x16x32_bf16 v[36:39], v[144:147], v[194:197], v[36:39]
	v_mfma_f32_16x16x32_bf16 v[32:35], v[152:155], v[194:197], v[32:35]
	v_mfma_f32_16x16x32_bf16 v[60:63], v[148:151], v[164:167], v[60:63]
	v_mfma_f32_16x16x32_bf16 v[56:59], v[156:159], v[164:167], v[56:59]
	v_mfma_f32_16x16x32_bf16 v[52:55], v[148:151], v[182:185], v[52:55]
	v_mfma_f32_16x16x32_bf16 v[48:51], v[156:159], v[182:185], v[48:51]
	v_mfma_f32_16x16x32_bf16 v[44:47], v[148:151], v[190:193], v[44:47]
	v_mfma_f32_16x16x32_bf16 v[40:43], v[156:159], v[190:193], v[40:43]
	v_mfma_f32_16x16x32_bf16 v[36:39], v[148:151], v[202:205], v[36:39]
	v_mfma_f32_16x16x32_bf16 v[32:35], v[156:159], v[202:205], v[32:35]
	s_barrier
	s_add_i32 s95, s95, s36
	v_lshl_add_u64 v[198:199], s[52:53], 0, v[200:201]
	s_mov_b32 m0, s95
	ds_read_b128 v[160:163], v242 offset:16384
	ds_read_b128 v[164:167], v242 offset:17408
	ds_read_b128 v[178:181], v242 offset:18432
	ds_read_b128 v[182:185], v242 offset:19456
	ds_read_b128 v[186:189], v242 offset:20480
	ds_read_b128 v[190:193], v242 offset:21504
	ds_read_b128 v[194:197], v242 offset:22528
	ds_read_b128 v[202:205], v242 offset:23552
	global_load_lds_dwordx4 v[198:199], off
	s_add_i32 m0, s95, 0x2000
	s_add_u32 vcc_lo, s52, 0x100000
	v_lshl_add_u64 v[206:207], s[52:53], 0, v[168:169]
	s_addc_u32 vcc_hi, s53, 0
	s_add_i32 s95, s96, s36
	global_load_lds_dwordx4 v[206:207], off
	v_lshl_add_u64 v[208:209], vcc, 0, v[200:201]
	s_mov_b32 m0, s95
	v_lshl_add_u64 v[210:211], s[74:75], 0, v[170:171]
	global_load_lds_dwordx4 v[208:209], off
	v_lshl_add_u64 v[208:209], vcc, 0, v[168:169]
	s_add_i32 m0, s95, 0x2000
	s_nop 0
	global_load_lds_dwordx4 v[208:209], off
	v_lshl_add_u64 v[208:209], s[74:75], 0, v[172:173]
	s_mov_b32 m0, s37
	s_nop 0
	global_load_lds_dwordx4 v[208:209], off
	s_mov_b32 m0, s38
	s_nop 0
	global_load_lds_dwordx4 v[210:211], off
	s_waitcnt vmcnt(8)
	s_waitcnt lgkmcnt(0)
	s_barrier
	s_waitcnt lgkmcnt(0)
	v_mfma_f32_16x16x32_bf16 v[92:95], v[128:131], v[160:163], v[92:95]
	v_mfma_f32_16x16x32_bf16 v[88:91], v[136:139], v[160:163], v[88:91]
	v_mfma_f32_16x16x32_bf16 v[84:87], v[128:131], v[178:181], v[84:87]
	v_mfma_f32_16x16x32_bf16 v[80:83], v[136:139], v[178:181], v[80:83]
	v_mfma_f32_16x16x32_bf16 v[76:79], v[128:131], v[186:189], v[76:79]
	v_mfma_f32_16x16x32_bf16 v[72:75], v[136:139], v[186:189], v[72:75]
	v_mfma_f32_16x16x32_bf16 v[68:71], v[128:131], v[194:197], v[68:71]
	v_mfma_f32_16x16x32_bf16 v[64:67], v[136:139], v[194:197], v[64:67]
	v_mfma_f32_16x16x32_bf16 v[92:95], v[132:135], v[164:167], v[92:95]
	v_mfma_f32_16x16x32_bf16 v[88:91], v[140:143], v[164:167], v[88:91]
	v_mfma_f32_16x16x32_bf16 v[84:87], v[132:135], v[182:185], v[84:87]
	v_mfma_f32_16x16x32_bf16 v[80:83], v[140:143], v[182:185], v[80:83]
	v_mfma_f32_16x16x32_bf16 v[76:79], v[132:135], v[190:193], v[76:79]
	v_mfma_f32_16x16x32_bf16 v[72:75], v[140:143], v[190:193], v[72:75]
	v_mfma_f32_16x16x32_bf16 v[68:71], v[132:135], v[202:205], v[68:71]
	v_mfma_f32_16x16x32_bf16 v[64:67], v[140:143], v[202:205], v[64:67]
	v_mfma_f32_16x16x32_bf16 v[28:31], v[144:147], v[160:163], v[28:31]
	v_mfma_f32_16x16x32_bf16 v[24:27], v[152:155], v[160:163], v[24:27]
	v_mfma_f32_16x16x32_bf16 v[20:23], v[144:147], v[178:181], v[20:23]
	v_mfma_f32_16x16x32_bf16 v[16:19], v[152:155], v[178:181], v[16:19]
	v_mfma_f32_16x16x32_bf16 v[12:15], v[144:147], v[186:189], v[12:15]
	v_mfma_f32_16x16x32_bf16 v[8:11], v[152:155], v[186:189], v[8:11]
	v_mfma_f32_16x16x32_bf16 v[4:7], v[144:147], v[194:197], v[4:7]
	v_mfma_f32_16x16x32_bf16 v[0:3], v[152:155], v[194:197], v[0:3]
	v_mfma_f32_16x16x32_bf16 v[28:31], v[148:151], v[164:167], v[28:31]
	v_mfma_f32_16x16x32_bf16 v[24:27], v[156:159], v[164:167], v[24:27]
	v_mfma_f32_16x16x32_bf16 v[20:23], v[148:151], v[182:185], v[20:23]
	v_mfma_f32_16x16x32_bf16 v[16:19], v[156:159], v[182:185], v[16:19]
	v_mfma_f32_16x16x32_bf16 v[12:15], v[148:151], v[190:193], v[12:15]
	v_mfma_f32_16x16x32_bf16 v[8:11], v[156:159], v[190:193], v[8:11]
	v_mfma_f32_16x16x32_bf16 v[4:7], v[148:151], v[202:205], v[4:7]
	v_mfma_f32_16x16x32_bf16 v[0:3], v[156:159], v[202:205], v[0:3]
	s_barrier
	s_add_i32 s95, 0, 0x18000
	s_add_i32 s96, 0, 0x1c000
	v_add_u32_e32 v140, s95, v225
	v_add_u32_e32 v156, s96, v225
	ds_read_b128 v[128:131], v140
	ds_read_b128 v[132:135], v140 offset:1024
	ds_read_b128 v[136:139], v140 offset:2048
	ds_read_b128 v[140:143], v140 offset:3072
	ds_read_b128 v[144:147], v156
	ds_read_b128 v[148:151], v156 offset:1024
	ds_read_b128 v[152:155], v156 offset:2048
	ds_read_b128 v[156:159], v156 offset:3072
	s_add_u32 s74, s74, 0x100000
	s_addc_u32 s75, s75, 0
	s_mov_b32 m0, s39
	v_lshl_add_u64 v[212:213], s[74:75], 0, v[172:173]
	ds_read_b128 v[160:163], v242 offset:32768
	ds_read_b128 v[164:167], v242 offset:33792
	ds_read_b128 v[178:181], v242 offset:34816
	ds_read_b128 v[182:185], v242 offset:35840
	ds_read_b128 v[186:189], v242 offset:36864
	ds_read_b128 v[190:193], v242 offset:37888
	ds_read_b128 v[194:197], v242 offset:38912
	ds_read_b128 v[202:205], v242 offset:39936
	global_load_lds_dwordx4 v[212:213], off
	v_lshl_add_u64 v[212:213], s[74:75], 0, v[170:171]
	s_mov_b32 m0, s40
	s_nop 0
	global_load_lds_dwordx4 v[212:213], off
	s_waitcnt vmcnt(8)
	s_waitcnt lgkmcnt(0)
	s_barrier
	s_waitcnt lgkmcnt(0)
	v_mfma_f32_16x16x32_bf16 v[104:107], v[128:131], v[160:163], v[104:107]
	v_mfma_f32_16x16x32_bf16 v[96:99], v[136:139], v[160:163], v[96:99]
	v_mfma_f32_16x16x32_bf16 v[120:123], v[128:131], v[178:181], v[120:123]
	v_mfma_f32_16x16x32_bf16 v[124:127], v[136:139], v[178:181], v[124:127]
	v_mfma_f32_16x16x32_bf16 v[116:119], v[128:131], v[186:189], v[116:119]
	v_mfma_f32_16x16x32_bf16 v[112:115], v[136:139], v[186:189], v[112:115]
	v_mfma_f32_16x16x32_bf16 v[108:111], v[128:131], v[194:197], v[108:111]
	v_mfma_f32_16x16x32_bf16 v[100:103], v[136:139], v[194:197], v[100:103]
	v_mfma_f32_16x16x32_bf16 v[104:107], v[132:135], v[164:167], v[104:107]
	v_mfma_f32_16x16x32_bf16 v[96:99], v[140:143], v[164:167], v[96:99]
	v_mfma_f32_16x16x32_bf16 v[120:123], v[132:135], v[182:185], v[120:123]
	v_mfma_f32_16x16x32_bf16 v[124:127], v[140:143], v[182:185], v[124:127]
	v_mfma_f32_16x16x32_bf16 v[116:119], v[132:135], v[190:193], v[116:119]
	v_mfma_f32_16x16x32_bf16 v[112:115], v[140:143], v[190:193], v[112:115]
	v_mfma_f32_16x16x32_bf16 v[108:111], v[132:135], v[202:205], v[108:111]
	v_mfma_f32_16x16x32_bf16 v[100:103], v[140:143], v[202:205], v[100:103]
	v_mfma_f32_16x16x32_bf16 v[60:63], v[144:147], v[160:163], v[60:63]
	v_mfma_f32_16x16x32_bf16 v[56:59], v[152:155], v[160:163], v[56:59]
	v_mfma_f32_16x16x32_bf16 v[52:55], v[144:147], v[178:181], v[52:55]
	v_mfma_f32_16x16x32_bf16 v[48:51], v[152:155], v[178:181], v[48:51]
	v_mfma_f32_16x16x32_bf16 v[44:47], v[144:147], v[186:189], v[44:47]
	v_mfma_f32_16x16x32_bf16 v[40:43], v[152:155], v[186:189], v[40:43]
	v_mfma_f32_16x16x32_bf16 v[36:39], v[144:147], v[194:197], v[36:39]
	v_mfma_f32_16x16x32_bf16 v[32:35], v[152:155], v[194:197], v[32:35]
	v_mfma_f32_16x16x32_bf16 v[60:63], v[148:151], v[164:167], v[60:63]
	v_mfma_f32_16x16x32_bf16 v[56:59], v[156:159], v[164:167], v[56:59]
	v_mfma_f32_16x16x32_bf16 v[52:55], v[148:151], v[182:185], v[52:55]
	v_mfma_f32_16x16x32_bf16 v[48:51], v[156:159], v[182:185], v[48:51]
	v_mfma_f32_16x16x32_bf16 v[44:47], v[148:151], v[190:193], v[44:47]
	v_mfma_f32_16x16x32_bf16 v[40:43], v[156:159], v[190:193], v[40:43]
	v_mfma_f32_16x16x32_bf16 v[36:39], v[148:151], v[202:205], v[36:39]
	v_mfma_f32_16x16x32_bf16 v[32:35], v[156:159], v[202:205], v[32:35]
	s_barrier
	s_add_i32 s74, s95, s36
	v_lshl_add_u64 v[198:199], v[198:199], 0, s[20:21]
	s_mov_b32 m0, s74
	ds_read_b128 v[160:163], v242 offset:49152
	ds_read_b128 v[164:167], v242 offset:50176
	ds_read_b128 v[178:181], v242 offset:51200
	ds_read_b128 v[182:185], v242 offset:52224
	ds_read_b128 v[186:189], v242 offset:53248
	ds_read_b128 v[190:193], v242 offset:54272
	ds_read_b128 v[194:197], v242 offset:55296
	ds_read_b128 v[202:205], v242 offset:56320
	global_load_lds_dwordx4 v[198:199], off
	s_add_i32 m0, s74, 0x2000
	s_add_u32 s52, s52, 0x100080
	v_lshl_add_u64 v[198:199], v[206:207], 0, s[20:21]
	s_addc_u32 s53, s53, 0
	s_add_i32 s74, s96, s36
	global_load_lds_dwordx4 v[198:199], off
	v_lshl_add_u64 v[198:199], s[52:53], 0, v[200:201]
	s_mov_b32 m0, s74
	s_nop 0
	global_load_lds_dwordx4 v[198:199], off
	v_lshl_add_u64 v[198:199], s[52:53], 0, v[168:169]
	s_add_i32 m0, s74, 0x2000
	s_nop 0
	global_load_lds_dwordx4 v[198:199], off
	v_lshl_add_u64 v[198:199], v[208:209], 0, s[20:21]
	s_mov_b32 m0, s89
	s_nop 0
	global_load_lds_dwordx4 v[198:199], off
	v_lshl_add_u64 v[198:199], v[210:211], 0, s[20:21]
	s_mov_b32 m0, s92
	s_nop 0
	global_load_lds_dwordx4 v[198:199], off
	s_waitcnt vmcnt(8)
	s_waitcnt lgkmcnt(0)
	s_barrier
	s_waitcnt lgkmcnt(0)
	v_mfma_f32_16x16x32_bf16 v[92:95], v[128:131], v[160:163], v[92:95]
	v_mfma_f32_16x16x32_bf16 v[88:91], v[136:139], v[160:163], v[88:91]
	v_mfma_f32_16x16x32_bf16 v[84:87], v[128:131], v[178:181], v[84:87]
	v_mfma_f32_16x16x32_bf16 v[80:83], v[136:139], v[178:181], v[80:83]
	v_mfma_f32_16x16x32_bf16 v[76:79], v[128:131], v[186:189], v[76:79]
	v_mfma_f32_16x16x32_bf16 v[72:75], v[136:139], v[186:189], v[72:75]
	v_mfma_f32_16x16x32_bf16 v[68:71], v[128:131], v[194:197], v[68:71]
	v_mfma_f32_16x16x32_bf16 v[64:67], v[136:139], v[194:197], v[64:67]
	v_mfma_f32_16x16x32_bf16 v[92:95], v[132:135], v[164:167], v[92:95]
	v_mfma_f32_16x16x32_bf16 v[88:91], v[140:143], v[164:167], v[88:91]
	v_mfma_f32_16x16x32_bf16 v[84:87], v[132:135], v[182:185], v[84:87]
	v_mfma_f32_16x16x32_bf16 v[80:83], v[140:143], v[182:185], v[80:83]
	v_mfma_f32_16x16x32_bf16 v[76:79], v[132:135], v[190:193], v[76:79]
	v_mfma_f32_16x16x32_bf16 v[72:75], v[140:143], v[190:193], v[72:75]
	v_mfma_f32_16x16x32_bf16 v[68:71], v[132:135], v[202:205], v[68:71]
	v_mfma_f32_16x16x32_bf16 v[64:67], v[140:143], v[202:205], v[64:67]
	v_mfma_f32_16x16x32_bf16 v[28:31], v[144:147], v[160:163], v[28:31]
	v_mfma_f32_16x16x32_bf16 v[24:27], v[152:155], v[160:163], v[24:27]
	v_mfma_f32_16x16x32_bf16 v[20:23], v[144:147], v[178:181], v[20:23]
	v_mfma_f32_16x16x32_bf16 v[16:19], v[152:155], v[178:181], v[16:19]
	v_mfma_f32_16x16x32_bf16 v[12:15], v[144:147], v[186:189], v[12:15]
	v_mfma_f32_16x16x32_bf16 v[8:11], v[152:155], v[186:189], v[8:11]
	v_mfma_f32_16x16x32_bf16 v[4:7], v[144:147], v[194:197], v[4:7]
	v_mfma_f32_16x16x32_bf16 v[0:3], v[152:155], v[194:197], v[0:3]
	v_mfma_f32_16x16x32_bf16 v[28:31], v[148:151], v[164:167], v[28:31]
	v_mfma_f32_16x16x32_bf16 v[24:27], v[156:159], v[164:167], v[24:27]
	v_mfma_f32_16x16x32_bf16 v[20:23], v[148:151], v[182:185], v[20:23]
	v_mfma_f32_16x16x32_bf16 v[16:19], v[156:159], v[182:185], v[16:19]
	v_mfma_f32_16x16x32_bf16 v[12:15], v[148:151], v[190:193], v[12:15]
	v_mfma_f32_16x16x32_bf16 v[8:11], v[156:159], v[190:193], v[8:11]
	v_mfma_f32_16x16x32_bf16 v[4:7], v[148:151], v[202:205], v[4:7]
	v_mfma_f32_16x16x32_bf16 v[0:3], v[156:159], v[202:205], v[0:3]
	s_barrier
	s_add_i32 s94, s94, 2
	s_add_u32 s10, s10, 0x100
	s_addc_u32 s11, s11, 0
	s_add_u32 s86, s86, 0x100
	s_addc_u32 s87, s87, 0
	s_cmp_gt_u32 s94, 61
	s_cbranch_scc0 .LBB0_1379
	s_and_b64 vcc, exec, s[72:73]
	s_cbranch_vccz .LBB0_1382
	s_barrier
